# added on the static-priority version: the leading wave group does not wait for its LDS reads before the pre-MFMA barrier
# baseline (speedup 1.0000x reference)
.LBB0_2:
	s_load_dword s33, s[0:1], 0xb0
	v_and_b32_e32 v195, 0x3ff, v0
	v_readfirstlane_b32 s32, v195
	v_readfirstlane_b32 s32, v195
	v_mov_b32_e32 v1, v195
	s_nop 0
	v_cmp_gt_i32_e32 vcc, 32, v1
	s_and_saveexec_b64 s[4:5], vcc
	s_cbranch_execz .LBB0_4
	v_mov_b32_e32 v1, v195
	v_mov_b32_e32 v2, 0
	v_lshl_add_u32 v1, v1, 2, 0
	v_add_u32_e32 v1, 0x20000, v1
	ds_write_b32 v1, v2

.Lsprio_0:
.LBB0_214:
	s_add_u32 s28, s30, 0xfffc0080
	s_addc_u32 s36, s31, -1
	s_add_i32 s43, 0, 0x10000
	s_cmp_eq_u32 s26, 12
	s_cselect_b32 s53, s2, s36
	s_cselect_b32 s52, s3, s28
	v_add_u32_e32 v157, s43, v153
	s_cselect_b32 s37, s13, s25
	s_cselect_b32 s36, s16, s24
	s_add_i32 s28, 0, 0x14000
	ds_read_b128 v[130:133], v157
	ds_read_b128 v[148:151], v157 offset:1024
	ds_read_b128 v[158:161], v157 offset:2048
	ds_read_b128 v[162:165], v157 offset:3072
	v_add_u32_e32 v157, s28, v153
	ds_read_b128 v[166:169], v157
	ds_read_b128 v[170:173], v157 offset:1024
	ds_read_b128 v[174:177], v157 offset:2048
	ds_read_b128 v[178:181], v157 offset:3072
	v_lshl_add_u64 v[192:193], s[30:31], 0, v[144:145]
	s_add_i32 m0, s75, 0xc000
	ds_read_b128 v[184:187], v156
	ds_read_b128 v[188:191], v156 offset:1024
	ds_read_b128 v[196:199], v156 offset:2048
	ds_read_b128 v[210:213], v156 offset:3072
	ds_read_b128 v[214:217], v156 offset:4096
	ds_read_b128 v[218:221], v156 offset:5120
	ds_read_b128 v[222:225], v156 offset:6144
	ds_read_b128 v[226:229], v156 offset:7168
	global_load_lds_dwordx4 v[192:193], off
	v_lshl_add_u64 v[192:193], s[30:31], 0, v[146:147]
	s_add_i32 m0, s75, 0xe000
	s_nop 0
	global_load_lds_dwordx4 v[192:193], off
	s_waitcnt vmcnt(8)
	s_cmp_lt_u32 s32, 0x100
	s_cbranch_scc1 .Llgk_skip_0
	s_waitcnt lgkmcnt(0)
.Llgk_skip_0:
	s_barrier
	s_waitcnt lgkmcnt(0)
	v_mfma_f32_16x16x32_bf16 v[126:129], v[130:133], v[184:187], v[126:129]
	v_mfma_f32_16x16x32_bf16 v[122:125], v[158:161], v[184:187], v[122:125]
	v_mfma_f32_16x16x32_bf16 v[110:113], v[130:133], v[196:199], v[110:113]
	v_mfma_f32_16x16x32_bf16 v[106:109], v[158:161], v[196:199], v[106:109]
	v_mfma_f32_16x16x32_bf16 v[94:97], v[130:133], v[214:217], v[94:97]
	v_mfma_f32_16x16x32_bf16 v[90:93], v[158:161], v[214:217], v[90:93]
	v_mfma_f32_16x16x32_bf16 v[78:81], v[130:133], v[222:225], v[78:81]
	v_mfma_f32_16x16x32_bf16 v[74:77], v[158:161], v[222:225], v[74:77]
	v_mfma_f32_16x16x32_bf16 v[126:129], v[148:151], v[188:191], v[126:129]
	v_mfma_f32_16x16x32_bf16 v[122:125], v[162:165], v[188:191], v[122:125]
	v_mfma_f32_16x16x32_bf16 v[110:113], v[148:151], v[210:213], v[110:113]
	v_mfma_f32_16x16x32_bf16 v[106:109], v[162:165], v[210:213], v[106:109]
	v_mfma_f32_16x16x32_bf16 v[94:97], v[148:151], v[218:221], v[94:97]
	v_mfma_f32_16x16x32_bf16 v[90:93], v[162:165], v[218:221], v[90:93]
	v_mfma_f32_16x16x32_bf16 v[78:81], v[148:151], v[226:229], v[78:81]
	v_mfma_f32_16x16x32_bf16 v[74:77], v[162:165], v[226:229], v[74:77]
	v_mfma_f32_16x16x32_bf16 v[118:121], v[166:169], v[184:187], v[118:121]
	v_mfma_f32_16x16x32_bf16 v[114:117], v[174:177], v[184:187], v[114:117]
	v_mfma_f32_16x16x32_bf16 v[102:105], v[166:169], v[196:199], v[102:105]
	v_mfma_f32_16x16x32_bf16 v[98:101], v[174:177], v[196:199], v[98:101]
	v_mfma_f32_16x16x32_bf16 v[86:89], v[166:169], v[214:217], v[86:89]
	v_mfma_f32_16x16x32_bf16 v[82:85], v[174:177], v[214:217], v[82:85]
	v_mfma_f32_16x16x32_bf16 v[70:73], v[166:169], v[222:225], v[70:73]
	v_mfma_f32_16x16x32_bf16 v[66:69], v[174:177], v[222:225], v[66:69]
	v_mfma_f32_16x16x32_bf16 v[118:121], v[170:173], v[188:191], v[118:121]
	v_mfma_f32_16x16x32_bf16 v[114:117], v[178:181], v[188:191], v[114:117]
	v_mfma_f32_16x16x32_bf16 v[102:105], v[170:173], v[210:213], v[102:105]
	v_mfma_f32_16x16x32_bf16 v[98:101], v[178:181], v[210:213], v[98:101]
	v_mfma_f32_16x16x32_bf16 v[86:89], v[170:173], v[218:221], v[86:89]
	v_mfma_f32_16x16x32_bf16 v[82:85], v[178:181], v[218:221], v[82:85]
	v_mfma_f32_16x16x32_bf16 v[70:73], v[170:173], v[226:229], v[70:73]
	v_mfma_f32_16x16x32_bf16 v[66:69], v[178:181], v[226:229], v[66:69]
	s_barrier
	s_add_i32 s43, s43, s17
	v_lshl_add_u64 v[192:193], s[36:37], 0, v[0:1]
	s_mov_b32 m0, s43
	ds_read_b128 v[184:187], v156 offset:16384
	ds_read_b128 v[188:191], v156 offset:17408
	ds_read_b128 v[196:199], v156 offset:18432
	ds_read_b128 v[210:213], v156 offset:19456
	ds_read_b128 v[214:217], v156 offset:20480
	ds_read_b128 v[218:221], v156 offset:21504
	ds_read_b128 v[222:225], v156 offset:22528
	ds_read_b128 v[226:229], v156 offset:23552
	global_load_lds_dwordx4 v[192:193], off
	s_add_i32 m0, s43, 0x2000
	s_add_u32 s70, s36, 0x40000
	v_lshl_add_u64 v[202:203], s[36:37], 0, v[134:135]
	s_addc_u32 s71, s37, 0
	s_add_i32 s28, s28, s17
	global_load_lds_dwordx4 v[202:203], off
	v_lshl_add_u64 v[230:231], s[70:71], 0, v[0:1]
	s_mov_b32 m0, s28
	v_lshl_add_u64 v[232:233], s[52:53], 0, v[136:137]
	global_load_lds_dwordx4 v[230:231], off
	v_lshl_add_u64 v[230:231], s[70:71], 0, v[134:135]
	s_add_i32 m0, s28, 0x2000
	s_nop 0
	global_load_lds_dwordx4 v[230:231], off
	v_lshl_add_u64 v[230:231], s[52:53], 0, v[138:139]
	s_mov_b32 m0, s75
	s_nop 0
	global_load_lds_dwordx4 v[230:231], off
	s_mov_b32 m0, s58
	s_nop 0
	global_load_lds_dwordx4 v[232:233], off
	s_waitcnt vmcnt(8)
	s_cmp_lt_u32 s32, 0x100
	s_cbranch_scc1 .Llgk_skip_1
	s_waitcnt lgkmcnt(0)
.Llgk_skip_1:
	s_barrier
	s_waitcnt lgkmcnt(0)
	v_mfma_f32_16x16x32_bf16 v[62:65], v[130:133], v[184:187], v[62:65]
	v_mfma_f32_16x16x32_bf16 v[58:61], v[158:161], v[184:187], v[58:61]
	v_mfma_f32_16x16x32_bf16 v[46:49], v[130:133], v[196:199], v[46:49]
	v_mfma_f32_16x16x32_bf16 v[42:45], v[158:161], v[196:199], v[42:45]
	v_mfma_f32_16x16x32_bf16 v[30:33], v[130:133], v[214:217], v[30:33]
	v_mfma_f32_16x16x32_bf16 v[26:29], v[158:161], v[214:217], v[26:29]
	v_mfma_f32_16x16x32_bf16 v[14:17], v[130:133], v[222:225], v[14:17]
	v_mfma_f32_16x16x32_bf16 v[10:13], v[158:161], v[222:225], v[10:13]
	v_mfma_f32_16x16x32_bf16 v[62:65], v[148:151], v[188:191], v[62:65]
	v_mfma_f32_16x16x32_bf16 v[58:61], v[162:165], v[188:191], v[58:61]
	v_mfma_f32_16x16x32_bf16 v[46:49], v[148:151], v[210:213], v[46:49]
	v_mfma_f32_16x16x32_bf16 v[42:45], v[162:165], v[210:213], v[42:45]
	v_mfma_f32_16x16x32_bf16 v[30:33], v[148:151], v[218:221], v[30:33]
	v_mfma_f32_16x16x32_bf16 v[26:29], v[162:165], v[218:221], v[26:29]
	v_mfma_f32_16x16x32_bf16 v[14:17], v[148:151], v[226:229], v[14:17]
	v_mfma_f32_16x16x32_bf16 v[10:13], v[162:165], v[226:229], v[10:13]
	v_mfma_f32_16x16x32_bf16 v[54:57], v[166:169], v[184:187], v[54:57]
	v_mfma_f32_16x16x32_bf16 v[50:53], v[174:177], v[184:187], v[50:53]
	v_mfma_f32_16x16x32_bf16 v[38:41], v[166:169], v[196:199], v[38:41]
	v_mfma_f32_16x16x32_bf16 v[34:37], v[174:177], v[196:199], v[34:37]
	v_mfma_f32_16x16x32_bf16 v[22:25], v[166:169], v[214:217], v[22:25]
	v_mfma_f32_16x16x32_bf16 v[18:21], v[174:177], v[214:217], v[18:21]
	v_mfma_f32_16x16x32_bf16 v[6:9], v[166:169], v[222:225], v[6:9]
	v_mfma_f32_16x16x32_bf16 v[2:5], v[174:177], v[222:225], v[2:5]
	v_mfma_f32_16x16x32_bf16 v[54:57], v[170:173], v[188:191], v[54:57]
	v_mfma_f32_16x16x32_bf16 v[50:53], v[178:181], v[188:191], v[50:53]
	v_mfma_f32_16x16x32_bf16 v[38:41], v[170:173], v[210:213], v[38:41]
	v_mfma_f32_16x16x32_bf16 v[34:37], v[178:181], v[210:213], v[34:37]
	v_mfma_f32_16x16x32_bf16 v[22:25], v[170:173], v[218:221], v[22:25]
	v_mfma_f32_16x16x32_bf16 v[18:21], v[178:181], v[218:221], v[18:21]
	v_mfma_f32_16x16x32_bf16 v[6:9], v[170:173], v[226:229], v[6:9]
	v_mfma_f32_16x16x32_bf16 v[2:5], v[178:181], v[226:229], v[2:5]
	s_barrier
	s_add_i32 s28, 0, 0x18000
	v_add_u32_e32 v157, s28, v153
	s_add_i32 s43, 0, 0x1c000
	ds_read_b128 v[130:133], v157
	ds_read_b128 v[148:151], v157 offset:1024
	ds_read_b128 v[158:161], v157 offset:2048
	ds_read_b128 v[162:165], v157 offset:3072
	v_add_u32_e32 v157, s43, v153
	ds_read_b128 v[166:169], v157
	ds_read_b128 v[170:173], v157 offset:1024
	ds_read_b128 v[174:177], v157 offset:2048
	ds_read_b128 v[178:181], v157 offset:3072
	s_add_u32 s52, s52, 0x40000
	s_addc_u32 s53, s53, 0
	s_mov_b32 m0, s59
	v_lshl_add_u64 v[234:235], s[52:53], 0, v[138:139]
	ds_read_b128 v[184:187], v156 offset:32768
	ds_read_b128 v[188:191], v156 offset:33792
	ds_read_b128 v[196:199], v156 offset:34816
	ds_read_b128 v[210:213], v156 offset:35840
	ds_read_b128 v[214:217], v156 offset:36864
	ds_read_b128 v[218:221], v156 offset:37888
	ds_read_b128 v[222:225], v156 offset:38912
	ds_read_b128 v[226:229], v156 offset:39936
	global_load_lds_dwordx4 v[234:235], off
	v_lshl_add_u64 v[234:235], s[52:53], 0, v[136:137]
	s_mov_b32 m0, s60
	s_nop 0
	global_load_lds_dwordx4 v[234:235], off
	s_waitcnt vmcnt(8)
	s_cmp_lt_u32 s32, 0x100
	s_cbranch_scc1 .Llgk_skip_2
	s_waitcnt lgkmcnt(0)
.Llgk_skip_2:
	s_barrier
	s_waitcnt lgkmcnt(0)
	v_mfma_f32_16x16x32_bf16 v[126:129], v[130:133], v[184:187], v[126:129]
	v_mfma_f32_16x16x32_bf16 v[122:125], v[158:161], v[184:187], v[122:125]
	v_mfma_f32_16x16x32_bf16 v[110:113], v[130:133], v[196:199], v[110:113]
	v_mfma_f32_16x16x32_bf16 v[106:109], v[158:161], v[196:199], v[106:109]
	v_mfma_f32_16x16x32_bf16 v[94:97], v[130:133], v[214:217], v[94:97]
	v_mfma_f32_16x16x32_bf16 v[90:93], v[158:161], v[214:217], v[90:93]
	v_mfma_f32_16x16x32_bf16 v[78:81], v[130:133], v[222:225], v[78:81]
	v_mfma_f32_16x16x32_bf16 v[74:77], v[158:161], v[222:225], v[74:77]
	v_mfma_f32_16x16x32_bf16 v[126:129], v[148:151], v[188:191], v[126:129]
	v_mfma_f32_16x16x32_bf16 v[122:125], v[162:165], v[188:191], v[122:125]
	v_mfma_f32_16x16x32_bf16 v[110:113], v[148:151], v[210:213], v[110:113]
	v_mfma_f32_16x16x32_bf16 v[106:109], v[162:165], v[210:213], v[106:109]
	v_mfma_f32_16x16x32_bf16 v[94:97], v[148:151], v[218:221], v[94:97]
	v_mfma_f32_16x16x32_bf16 v[90:93], v[162:165], v[218:221], v[90:93]
	v_mfma_f32_16x16x32_bf16 v[78:81], v[148:151], v[226:229], v[78:81]
	v_mfma_f32_16x16x32_bf16 v[74:77], v[162:165], v[226:229], v[74:77]
	v_mfma_f32_16x16x32_bf16 v[118:121], v[166:169], v[184:187], v[118:121]
	v_mfma_f32_16x16x32_bf16 v[114:117], v[174:177], v[184:187], v[114:117]
	v_mfma_f32_16x16x32_bf16 v[102:105], v[166:169], v[196:199], v[102:105]
	v_mfma_f32_16x16x32_bf16 v[98:101], v[174:177], v[196:199], v[98:101]
	v_mfma_f32_16x16x32_bf16 v[86:89], v[166:169], v[214:217], v[86:89]
	v_mfma_f32_16x16x32_bf16 v[82:85], v[174:177], v[214:217], v[82:85]
	v_mfma_f32_16x16x32_bf16 v[70:73], v[166:169], v[222:225], v[70:73]
	v_mfma_f32_16x16x32_bf16 v[66:69], v[174:177], v[222:225], v[66:69]
	v_mfma_f32_16x16x32_bf16 v[118:121], v[170:173], v[188:191], v[118:121]
	v_mfma_f32_16x16x32_bf16 v[114:117], v[178:181], v[188:191], v[114:117]
	v_mfma_f32_16x16x32_bf16 v[102:105], v[170:173], v[210:213], v[102:105]
	v_mfma_f32_16x16x32_bf16 v[98:101], v[178:181], v[210:213], v[98:101]
	v_mfma_f32_16x16x32_bf16 v[86:89], v[170:173], v[218:221], v[86:89]
	v_mfma_f32_16x16x32_bf16 v[82:85], v[178:181], v[218:221], v[82:85]
	v_mfma_f32_16x16x32_bf16 v[70:73], v[170:173], v[226:229], v[70:73]
	v_mfma_f32_16x16x32_bf16 v[66:69], v[178:181], v[226:229], v[66:69]
	s_barrier
	s_add_i32 s28, s28, s17
	v_lshl_add_u64 v[192:193], v[192:193], 0, s[22:23]
	s_mov_b32 m0, s28
	ds_read_b128 v[184:187], v156 offset:49152
	ds_read_b128 v[188:191], v156 offset:50176
	ds_read_b128 v[196:199], v156 offset:51200
	ds_read_b128 v[210:213], v156 offset:52224
	ds_read_b128 v[214:217], v156 offset:53248
	ds_read_b128 v[218:221], v156 offset:54272
	ds_read_b128 v[222:225], v156 offset:55296
	ds_read_b128 v[226:229], v156 offset:56320
	global_load_lds_dwordx4 v[192:193], off
	s_add_i32 m0, s28, 0x2000
	s_add_u32 s36, s36, 0x40080
	v_lshl_add_u64 v[192:193], v[202:203], 0, s[22:23]
	s_addc_u32 s37, s37, 0
	s_add_i32 s28, s43, s17
	global_load_lds_dwordx4 v[192:193], off
	v_lshl_add_u64 v[192:193], s[36:37], 0, v[0:1]
	s_mov_b32 m0, s28
	s_nop 0
	global_load_lds_dwordx4 v[192:193], off
	v_lshl_add_u64 v[192:193], s[36:37], 0, v[134:135]
	s_add_i32 m0, s28, 0x2000
	s_nop 0
	global_load_lds_dwordx4 v[192:193], off
	v_lshl_add_u64 v[192:193], v[230:231], 0, s[22:23]
	s_mov_b32 m0, s62
	s_nop 0
	global_load_lds_dwordx4 v[192:193], off
	v_lshl_add_u64 v[192:193], v[232:233], 0, s[22:23]
	s_mov_b32 m0, s63
	s_nop 0
	global_load_lds_dwordx4 v[192:193], off
	s_waitcnt vmcnt(8)
	s_cmp_lt_u32 s32, 0x100
	s_cbranch_scc1 .Llgk_skip_3
	s_waitcnt lgkmcnt(0)
.Llgk_skip_3:
	s_barrier
	s_waitcnt lgkmcnt(0)
	v_mfma_f32_16x16x32_bf16 v[62:65], v[130:133], v[184:187], v[62:65]
	v_mfma_f32_16x16x32_bf16 v[58:61], v[158:161], v[184:187], v[58:61]
	v_mfma_f32_16x16x32_bf16 v[46:49], v[130:133], v[196:199], v[46:49]
	v_mfma_f32_16x16x32_bf16 v[42:45], v[158:161], v[196:199], v[42:45]
	v_mfma_f32_16x16x32_bf16 v[30:33], v[130:133], v[214:217], v[30:33]
	v_mfma_f32_16x16x32_bf16 v[26:29], v[158:161], v[214:217], v[26:29]
	v_mfma_f32_16x16x32_bf16 v[14:17], v[130:133], v[222:225], v[14:17]
	v_mfma_f32_16x16x32_bf16 v[10:13], v[158:161], v[222:225], v[10:13]
	v_mfma_f32_16x16x32_bf16 v[62:65], v[148:151], v[188:191], v[62:65]
	v_mfma_f32_16x16x32_bf16 v[58:61], v[162:165], v[188:191], v[58:61]
	v_mfma_f32_16x16x32_bf16 v[46:49], v[148:151], v[210:213], v[46:49]
	v_mfma_f32_16x16x32_bf16 v[42:45], v[162:165], v[210:213], v[42:45]
	v_mfma_f32_16x16x32_bf16 v[30:33], v[148:151], v[218:221], v[30:33]
	v_mfma_f32_16x16x32_bf16 v[26:29], v[162:165], v[218:221], v[26:29]
	v_mfma_f32_16x16x32_bf16 v[14:17], v[148:151], v[226:229], v[14:17]
	v_mfma_f32_16x16x32_bf16 v[10:13], v[162:165], v[226:229], v[10:13]
	v_mfma_f32_16x16x32_bf16 v[54:57], v[166:169], v[184:187], v[54:57]
	v_mfma_f32_16x16x32_bf16 v[50:53], v[174:177], v[184:187], v[50:53]
	v_mfma_f32_16x16x32_bf16 v[38:41], v[166:169], v[196:199], v[38:41]
	v_mfma_f32_16x16x32_bf16 v[34:37], v[174:177], v[196:199], v[34:37]
	v_mfma_f32_16x16x32_bf16 v[22:25], v[166:169], v[214:217], v[22:25]
	v_mfma_f32_16x16x32_bf16 v[18:21], v[174:177], v[214:217], v[18:21]
	v_mfma_f32_16x16x32_bf16 v[6:9], v[166:169], v[222:225], v[6:9]
	v_mfma_f32_16x16x32_bf16 v[2:5], v[174:177], v[222:225], v[2:5]
	v_mfma_f32_16x16x32_bf16 v[54:57], v[170:173], v[188:191], v[54:57]
	v_mfma_f32_16x16x32_bf16 v[50:53], v[178:181], v[188:191], v[50:53]
	v_mfma_f32_16x16x32_bf16 v[38:41], v[170:173], v[210:213], v[38:41]
	v_mfma_f32_16x16x32_bf16 v[34:37], v[178:181], v[210:213], v[34:37]
	v_mfma_f32_16x16x32_bf16 v[22:25], v[170:173], v[218:221], v[22:25]
	v_mfma_f32_16x16x32_bf16 v[18:21], v[178:181], v[218:221], v[18:21]
	v_mfma_f32_16x16x32_bf16 v[6:9], v[170:173], v[226:229], v[6:9]
	v_mfma_f32_16x16x32_bf16 v[2:5], v[178:181], v[226:229], v[2:5]
	s_barrier
	s_add_i32 s26, s26, 2
	s_add_u32 s30, s30, 0x100
	s_addc_u32 s31, s31, 0
	s_add_u32 s24, s24, 0x100
	s_addc_u32 s25, s25, 0
	s_cmp_gt_u32 s26, 13
	s_cbranch_scc0 .LBB0_214
	s_setprio 0
	s_and_b64 vcc, exec, s[34:35]
	s_cbranch_vccz .LBB0_227
	s_barrier
	v_lshl_add_u32 v148, s12, 8, v152
	s_cmp_lt_i32 s74, s64
	s_mov_b64 s[12:13], -1
	s_cbranch_scc0 .LBB0_228

.Lsprio_1:
.LBB0_695:
	s_add_u32 s30, s12, 0xfffc0080
	s_addc_u32 s31, s13, -1
	s_add_i32 s45, 0, 0x10000
	s_cmp_eq_u32 s35, 12
	s_cselect_b32 s37, s3, s31
	s_cselect_b32 s36, s16, s30
	s_cselect_b32 s31, s24, s28
	s_cselect_b32 s30, s25, s26
	s_add_i32 s59, 0, 0x14000
	v_add_u32_e32 v156, s45, v145
	v_add_u32_e32 v172, s59, v145
	ds_read_b128 v[140:143], v156
	ds_read_b128 v[148:151], v156 offset:1024
	ds_read_b128 v[152:155], v156 offset:2048
	ds_read_b128 v[156:159], v156 offset:3072
	ds_read_b128 v[160:163], v172
	ds_read_b128 v[164:167], v172 offset:1024
	ds_read_b128 v[168:171], v172 offset:2048
	ds_read_b128 v[172:175], v172 offset:3072
	v_lshl_add_u64 v[180:181], s[12:13], 0, v[136:137]
	s_add_i32 m0, s51, 0xc000
	ds_read_b128 v[176:179], v147
	ds_read_b128 v[184:187], v147 offset:1024
	ds_read_b128 v[188:191], v147 offset:2048
	ds_read_b128 v[196:199], v147 offset:3072
	ds_read_b128 v[210:213], v147 offset:4096
	ds_read_b128 v[214:217], v147 offset:5120
	ds_read_b128 v[218:221], v147 offset:6144
	ds_read_b128 v[222:225], v147 offset:7168
	global_load_lds_dwordx4 v[180:181], off
	v_lshl_add_u64 v[180:181], s[12:13], 0, v[138:139]
	s_add_i32 m0, s51, 0xe000
	s_nop 0
	global_load_lds_dwordx4 v[180:181], off
	s_waitcnt vmcnt(8)
	s_cmp_lt_u32 s32, 0x100
	s_cbranch_scc1 .Llgk_skip_4
	s_waitcnt lgkmcnt(0)
.Llgk_skip_4:
	s_barrier
	s_waitcnt lgkmcnt(0)
	v_mfma_f32_16x16x32_bf16 v[126:129], v[140:143], v[176:179], v[126:129]
	v_mfma_f32_16x16x32_bf16 v[122:125], v[152:155], v[176:179], v[122:125]
	v_mfma_f32_16x16x32_bf16 v[110:113], v[140:143], v[188:191], v[110:113]
	v_mfma_f32_16x16x32_bf16 v[106:109], v[152:155], v[188:191], v[106:109]
	v_mfma_f32_16x16x32_bf16 v[94:97], v[140:143], v[210:213], v[94:97]
	v_mfma_f32_16x16x32_bf16 v[90:93], v[152:155], v[210:213], v[90:93]
	v_mfma_f32_16x16x32_bf16 v[78:81], v[140:143], v[218:221], v[78:81]
	v_mfma_f32_16x16x32_bf16 v[74:77], v[152:155], v[218:221], v[74:77]
	v_mfma_f32_16x16x32_bf16 v[126:129], v[148:151], v[184:187], v[126:129]
	v_mfma_f32_16x16x32_bf16 v[122:125], v[156:159], v[184:187], v[122:125]
	v_mfma_f32_16x16x32_bf16 v[110:113], v[148:151], v[196:199], v[110:113]
	v_mfma_f32_16x16x32_bf16 v[106:109], v[156:159], v[196:199], v[106:109]
	v_mfma_f32_16x16x32_bf16 v[94:97], v[148:151], v[214:217], v[94:97]
	v_mfma_f32_16x16x32_bf16 v[90:93], v[156:159], v[214:217], v[90:93]
	v_mfma_f32_16x16x32_bf16 v[78:81], v[148:151], v[222:225], v[78:81]
	v_mfma_f32_16x16x32_bf16 v[74:77], v[156:159], v[222:225], v[74:77]
	v_mfma_f32_16x16x32_bf16 v[118:121], v[160:163], v[176:179], v[118:121]
	v_mfma_f32_16x16x32_bf16 v[114:117], v[168:171], v[176:179], v[114:117]
	v_mfma_f32_16x16x32_bf16 v[102:105], v[160:163], v[188:191], v[102:105]
	v_mfma_f32_16x16x32_bf16 v[98:101], v[168:171], v[188:191], v[98:101]
	v_mfma_f32_16x16x32_bf16 v[86:89], v[160:163], v[210:213], v[86:89]
	v_mfma_f32_16x16x32_bf16 v[82:85], v[168:171], v[210:213], v[82:85]
	v_mfma_f32_16x16x32_bf16 v[70:73], v[160:163], v[218:221], v[70:73]
	v_mfma_f32_16x16x32_bf16 v[66:69], v[168:171], v[218:221], v[66:69]
	v_mfma_f32_16x16x32_bf16 v[118:121], v[164:167], v[184:187], v[118:121]
	v_mfma_f32_16x16x32_bf16 v[114:117], v[172:175], v[184:187], v[114:117]
	v_mfma_f32_16x16x32_bf16 v[102:105], v[164:167], v[196:199], v[102:105]
	v_mfma_f32_16x16x32_bf16 v[98:101], v[172:175], v[196:199], v[98:101]
	v_mfma_f32_16x16x32_bf16 v[86:89], v[164:167], v[214:217], v[86:89]
	v_mfma_f32_16x16x32_bf16 v[82:85], v[172:175], v[214:217], v[82:85]
	v_mfma_f32_16x16x32_bf16 v[70:73], v[164:167], v[222:225], v[70:73]
	v_mfma_f32_16x16x32_bf16 v[66:69], v[172:175], v[222:225], v[66:69]
	s_barrier
	s_add_i32 s45, s45, s50
	v_lshl_add_u64 v[180:181], s[30:31], 0, v[0:1]
	s_mov_b32 m0, s45
	ds_read_b128 v[176:179], v147 offset:16384
	ds_read_b128 v[184:187], v147 offset:17408
	ds_read_b128 v[188:191], v147 offset:18432
	ds_read_b128 v[196:199], v147 offset:19456
	ds_read_b128 v[210:213], v147 offset:20480
	ds_read_b128 v[214:217], v147 offset:21504
	ds_read_b128 v[218:221], v147 offset:22528
	ds_read_b128 v[222:225], v147 offset:23552
	global_load_lds_dwordx4 v[180:181], off
	s_add_i32 m0, s45, 0x2000
	s_add_u32 s60, s30, 0x40000
	v_lshl_add_u64 v[192:193], s[30:31], 0, v[130:131]
	s_addc_u32 s61, s31, 0
	s_add_i32 s45, s59, s50
	global_load_lds_dwordx4 v[192:193], off
	v_lshl_add_u64 v[202:203], s[60:61], 0, v[0:1]
	s_mov_b32 m0, s45
	v_lshl_add_u64 v[226:227], s[36:37], 0, v[132:133]
	global_load_lds_dwordx4 v[202:203], off
	v_lshl_add_u64 v[202:203], s[60:61], 0, v[130:131]
	s_add_i32 m0, s45, 0x2000
	s_nop 0
	global_load_lds_dwordx4 v[202:203], off
	v_lshl_add_u64 v[202:203], s[36:37], 0, v[134:135]
	s_mov_b32 m0, s51
	s_nop 0
	global_load_lds_dwordx4 v[202:203], off
	s_mov_b32 m0, s52
	s_nop 0
	global_load_lds_dwordx4 v[226:227], off
	s_waitcnt vmcnt(8)
	s_cmp_lt_u32 s32, 0x100
	s_cbranch_scc1 .Llgk_skip_5
	s_waitcnt lgkmcnt(0)
.Llgk_skip_5:
	s_barrier
	s_waitcnt lgkmcnt(0)
	v_mfma_f32_16x16x32_bf16 v[62:65], v[140:143], v[176:179], v[62:65]
	v_mfma_f32_16x16x32_bf16 v[58:61], v[152:155], v[176:179], v[58:61]
	v_mfma_f32_16x16x32_bf16 v[46:49], v[140:143], v[188:191], v[46:49]
	v_mfma_f32_16x16x32_bf16 v[42:45], v[152:155], v[188:191], v[42:45]
	v_mfma_f32_16x16x32_bf16 v[30:33], v[140:143], v[210:213], v[30:33]
	v_mfma_f32_16x16x32_bf16 v[26:29], v[152:155], v[210:213], v[26:29]
	v_mfma_f32_16x16x32_bf16 v[14:17], v[140:143], v[218:221], v[14:17]
	v_mfma_f32_16x16x32_bf16 v[10:13], v[152:155], v[218:221], v[10:13]
	v_mfma_f32_16x16x32_bf16 v[62:65], v[148:151], v[184:187], v[62:65]
	v_mfma_f32_16x16x32_bf16 v[58:61], v[156:159], v[184:187], v[58:61]
	v_mfma_f32_16x16x32_bf16 v[46:49], v[148:151], v[196:199], v[46:49]
	v_mfma_f32_16x16x32_bf16 v[42:45], v[156:159], v[196:199], v[42:45]
	v_mfma_f32_16x16x32_bf16 v[30:33], v[148:151], v[214:217], v[30:33]
	v_mfma_f32_16x16x32_bf16 v[26:29], v[156:159], v[214:217], v[26:29]
	v_mfma_f32_16x16x32_bf16 v[14:17], v[148:151], v[222:225], v[14:17]
	v_mfma_f32_16x16x32_bf16 v[10:13], v[156:159], v[222:225], v[10:13]
	v_mfma_f32_16x16x32_bf16 v[54:57], v[160:163], v[176:179], v[54:57]
	v_mfma_f32_16x16x32_bf16 v[50:53], v[168:171], v[176:179], v[50:53]
	v_mfma_f32_16x16x32_bf16 v[38:41], v[160:163], v[188:191], v[38:41]
	v_mfma_f32_16x16x32_bf16 v[34:37], v[168:171], v[188:191], v[34:37]
	v_mfma_f32_16x16x32_bf16 v[22:25], v[160:163], v[210:213], v[22:25]
	v_mfma_f32_16x16x32_bf16 v[18:21], v[168:171], v[210:213], v[18:21]
	v_mfma_f32_16x16x32_bf16 v[6:9], v[160:163], v[218:221], v[6:9]
	v_mfma_f32_16x16x32_bf16 v[2:5], v[168:171], v[218:221], v[2:5]
	v_mfma_f32_16x16x32_bf16 v[54:57], v[164:167], v[184:187], v[54:57]
	v_mfma_f32_16x16x32_bf16 v[50:53], v[172:175], v[184:187], v[50:53]
	v_mfma_f32_16x16x32_bf16 v[38:41], v[164:167], v[196:199], v[38:41]
	v_mfma_f32_16x16x32_bf16 v[34:37], v[172:175], v[196:199], v[34:37]
	v_mfma_f32_16x16x32_bf16 v[22:25], v[164:167], v[214:217], v[22:25]
	v_mfma_f32_16x16x32_bf16 v[18:21], v[172:175], v[214:217], v[18:21]
	v_mfma_f32_16x16x32_bf16 v[6:9], v[164:167], v[222:225], v[6:9]
	v_mfma_f32_16x16x32_bf16 v[2:5], v[172:175], v[222:225], v[2:5]
	s_barrier
	s_add_i32 s45, 0, 0x18000
	s_add_i32 s59, 0, 0x1c000
	v_add_u32_e32 v156, s45, v145
	v_add_u32_e32 v172, s59, v145
	ds_read_b128 v[140:143], v156
	ds_read_b128 v[148:151], v156 offset:1024
	ds_read_b128 v[152:155], v156 offset:2048
	ds_read_b128 v[156:159], v156 offset:3072
	ds_read_b128 v[160:163], v172
	ds_read_b128 v[164:167], v172 offset:1024
	ds_read_b128 v[168:171], v172 offset:2048
	ds_read_b128 v[172:175], v172 offset:3072
	s_add_u32 s36, s36, 0x40000
	s_addc_u32 s37, s37, 0
	s_mov_b32 m0, s53
	v_lshl_add_u64 v[228:229], s[36:37], 0, v[134:135]
	ds_read_b128 v[176:179], v147 offset:32768
	ds_read_b128 v[184:187], v147 offset:33792
	ds_read_b128 v[188:191], v147 offset:34816
	ds_read_b128 v[196:199], v147 offset:35840
	ds_read_b128 v[210:213], v147 offset:36864
	ds_read_b128 v[214:217], v147 offset:37888
	ds_read_b128 v[218:221], v147 offset:38912
	ds_read_b128 v[222:225], v147 offset:39936
	global_load_lds_dwordx4 v[228:229], off
	v_lshl_add_u64 v[228:229], s[36:37], 0, v[132:133]
	s_mov_b32 m0, s54
	s_nop 0
	global_load_lds_dwordx4 v[228:229], off
	s_waitcnt vmcnt(8)
	s_cmp_lt_u32 s32, 0x100
	s_cbranch_scc1 .Llgk_skip_6
	s_waitcnt lgkmcnt(0)
.Llgk_skip_6:
	s_barrier
	s_waitcnt lgkmcnt(0)
	v_mfma_f32_16x16x32_bf16 v[126:129], v[140:143], v[176:179], v[126:129]
	v_mfma_f32_16x16x32_bf16 v[122:125], v[152:155], v[176:179], v[122:125]
	v_mfma_f32_16x16x32_bf16 v[110:113], v[140:143], v[188:191], v[110:113]
	v_mfma_f32_16x16x32_bf16 v[106:109], v[152:155], v[188:191], v[106:109]
	v_mfma_f32_16x16x32_bf16 v[94:97], v[140:143], v[210:213], v[94:97]
	v_mfma_f32_16x16x32_bf16 v[90:93], v[152:155], v[210:213], v[90:93]
	v_mfma_f32_16x16x32_bf16 v[78:81], v[140:143], v[218:221], v[78:81]
	v_mfma_f32_16x16x32_bf16 v[74:77], v[152:155], v[218:221], v[74:77]
	v_mfma_f32_16x16x32_bf16 v[126:129], v[148:151], v[184:187], v[126:129]
	v_mfma_f32_16x16x32_bf16 v[122:125], v[156:159], v[184:187], v[122:125]
	v_mfma_f32_16x16x32_bf16 v[110:113], v[148:151], v[196:199], v[110:113]
	v_mfma_f32_16x16x32_bf16 v[106:109], v[156:159], v[196:199], v[106:109]
	v_mfma_f32_16x16x32_bf16 v[94:97], v[148:151], v[214:217], v[94:97]
	v_mfma_f32_16x16x32_bf16 v[90:93], v[156:159], v[214:217], v[90:93]
	v_mfma_f32_16x16x32_bf16 v[78:81], v[148:151], v[222:225], v[78:81]
	v_mfma_f32_16x16x32_bf16 v[74:77], v[156:159], v[222:225], v[74:77]
	v_mfma_f32_16x16x32_bf16 v[118:121], v[160:163], v[176:179], v[118:121]
	v_mfma_f32_16x16x32_bf16 v[114:117], v[168:171], v[176:179], v[114:117]
	v_mfma_f32_16x16x32_bf16 v[102:105], v[160:163], v[188:191], v[102:105]
	v_mfma_f32_16x16x32_bf16 v[98:101], v[168:171], v[188:191], v[98:101]
	v_mfma_f32_16x16x32_bf16 v[86:89], v[160:163], v[210:213], v[86:89]
	v_mfma_f32_16x16x32_bf16 v[82:85], v[168:171], v[210:213], v[82:85]
	v_mfma_f32_16x16x32_bf16 v[70:73], v[160:163], v[218:221], v[70:73]
	v_mfma_f32_16x16x32_bf16 v[66:69], v[168:171], v[218:221], v[66:69]
	v_mfma_f32_16x16x32_bf16 v[118:121], v[164:167], v[184:187], v[118:121]
	v_mfma_f32_16x16x32_bf16 v[114:117], v[172:175], v[184:187], v[114:117]
	v_mfma_f32_16x16x32_bf16 v[102:105], v[164:167], v[196:199], v[102:105]
	v_mfma_f32_16x16x32_bf16 v[98:101], v[172:175], v[196:199], v[98:101]
	v_mfma_f32_16x16x32_bf16 v[86:89], v[164:167], v[214:217], v[86:89]
	v_mfma_f32_16x16x32_bf16 v[82:85], v[172:175], v[214:217], v[82:85]
	v_mfma_f32_16x16x32_bf16 v[70:73], v[164:167], v[222:225], v[70:73]
	v_mfma_f32_16x16x32_bf16 v[66:69], v[172:175], v[222:225], v[66:69]
	s_barrier
	s_add_i32 s36, s45, s50
	v_lshl_add_u64 v[180:181], v[180:181], 0, s[22:23]
	s_mov_b32 m0, s36
	ds_read_b128 v[176:179], v147 offset:49152
	ds_read_b128 v[184:187], v147 offset:50176
	ds_read_b128 v[188:191], v147 offset:51200
	ds_read_b128 v[196:199], v147 offset:52224
	ds_read_b128 v[210:213], v147 offset:53248
	ds_read_b128 v[214:217], v147 offset:54272
	ds_read_b128 v[218:221], v147 offset:55296
	ds_read_b128 v[222:225], v147 offset:56320
	global_load_lds_dwordx4 v[180:181], off
	s_add_i32 m0, s36, 0x2000
	s_add_u32 s30, s30, 0x40080
	v_lshl_add_u64 v[180:181], v[192:193], 0, s[22:23]
	s_addc_u32 s31, s31, 0
	s_add_i32 s36, s59, s50
	global_load_lds_dwordx4 v[180:181], off
	v_lshl_add_u64 v[180:181], s[30:31], 0, v[0:1]
	s_mov_b32 m0, s36
	s_nop 0
	global_load_lds_dwordx4 v[180:181], off
	v_lshl_add_u64 v[180:181], s[30:31], 0, v[130:131]
	s_add_i32 m0, s36, 0x2000
	s_nop 0
	global_load_lds_dwordx4 v[180:181], off
	v_lshl_add_u64 v[180:181], v[202:203], 0, s[22:23]
	s_mov_b32 m0, s56
	s_nop 0
	global_load_lds_dwordx4 v[180:181], off
	v_lshl_add_u64 v[180:181], v[226:227], 0, s[22:23]
	s_mov_b32 m0, s57
	s_nop 0
	global_load_lds_dwordx4 v[180:181], off
	s_waitcnt vmcnt(8)
	s_cmp_lt_u32 s32, 0x100
	s_cbranch_scc1 .Llgk_skip_7
	s_waitcnt lgkmcnt(0)
.Llgk_skip_7:
	s_barrier
	s_waitcnt lgkmcnt(0)
	v_mfma_f32_16x16x32_bf16 v[62:65], v[140:143], v[176:179], v[62:65]
	v_mfma_f32_16x16x32_bf16 v[58:61], v[152:155], v[176:179], v[58:61]
	v_mfma_f32_16x16x32_bf16 v[46:49], v[140:143], v[188:191], v[46:49]
	v_mfma_f32_16x16x32_bf16 v[42:45], v[152:155], v[188:191], v[42:45]
	v_mfma_f32_16x16x32_bf16 v[30:33], v[140:143], v[210:213], v[30:33]
	v_mfma_f32_16x16x32_bf16 v[26:29], v[152:155], v[210:213], v[26:29]
	v_mfma_f32_16x16x32_bf16 v[14:17], v[140:143], v[218:221], v[14:17]
	v_mfma_f32_16x16x32_bf16 v[10:13], v[152:155], v[218:221], v[10:13]
	v_mfma_f32_16x16x32_bf16 v[62:65], v[148:151], v[184:187], v[62:65]
	v_mfma_f32_16x16x32_bf16 v[58:61], v[156:159], v[184:187], v[58:61]
	v_mfma_f32_16x16x32_bf16 v[46:49], v[148:151], v[196:199], v[46:49]
	v_mfma_f32_16x16x32_bf16 v[42:45], v[156:159], v[196:199], v[42:45]
	v_mfma_f32_16x16x32_bf16 v[30:33], v[148:151], v[214:217], v[30:33]
	v_mfma_f32_16x16x32_bf16 v[26:29], v[156:159], v[214:217], v[26:29]
	v_mfma_f32_16x16x32_bf16 v[14:17], v[148:151], v[222:225], v[14:17]
	v_mfma_f32_16x16x32_bf16 v[10:13], v[156:159], v[222:225], v[10:13]
	v_mfma_f32_16x16x32_bf16 v[54:57], v[160:163], v[176:179], v[54:57]
	v_mfma_f32_16x16x32_bf16 v[50:53], v[168:171], v[176:179], v[50:53]
	v_mfma_f32_16x16x32_bf16 v[38:41], v[160:163], v[188:191], v[38:41]
	v_mfma_f32_16x16x32_bf16 v[34:37], v[168:171], v[188:191], v[34:37]
	v_mfma_f32_16x16x32_bf16 v[22:25], v[160:163], v[210:213], v[22:25]
	v_mfma_f32_16x16x32_bf16 v[18:21], v[168:171], v[210:213], v[18:21]
	v_mfma_f32_16x16x32_bf16 v[6:9], v[160:163], v[218:221], v[6:9]
	v_mfma_f32_16x16x32_bf16 v[2:5], v[168:171], v[218:221], v[2:5]
	v_mfma_f32_16x16x32_bf16 v[54:57], v[164:167], v[184:187], v[54:57]
	v_mfma_f32_16x16x32_bf16 v[50:53], v[172:175], v[184:187], v[50:53]
	v_mfma_f32_16x16x32_bf16 v[38:41], v[164:167], v[196:199], v[38:41]
	v_mfma_f32_16x16x32_bf16 v[34:37], v[172:175], v[196:199], v[34:37]
	v_mfma_f32_16x16x32_bf16 v[22:25], v[164:167], v[214:217], v[22:25]
	v_mfma_f32_16x16x32_bf16 v[18:21], v[172:175], v[214:217], v[18:21]
	v_mfma_f32_16x16x32_bf16 v[6:9], v[164:167], v[222:225], v[6:9]
	v_mfma_f32_16x16x32_bf16 v[2:5], v[172:175], v[222:225], v[2:5]
	s_barrier
	s_add_i32 s35, s35, 2
	s_add_u32 s12, s12, 0x100
	s_addc_u32 s13, s13, 0
	s_add_u32 s26, s26, 0x100
	s_addc_u32 s28, s28, 0
	s_cmp_gt_u32 s35, 13
	s_cbranch_scc0 .LBB0_695
	s_setprio 0
	s_and_b64 vcc, exec, s[20:21]
	s_cbranch_vccz .LBB0_698
	s_barrier

.Lsprio_2:
.LBB0_792:
	s_add_u32 s36, s34, 0xfffc0080
	s_addc_u32 s37, s35, -1
	s_add_i32 s51, 0, 0x10000
	s_cmp_eq_u32 s50, 12
	s_cselect_b32 s41, s15, s37
	s_cselect_b32 s40, s46, s36
	v_add_u32_e32 v149, s51, v145
	s_cselect_b32 s37, s13, s49
	s_cselect_b32 s36, s47, s48
	s_add_i32 s54, 0, 0x14000
	ds_read_b128 v[140:143], v149
	ds_read_b128 v[150:153], v149 offset:1024
	ds_read_b128 v[154:157], v149 offset:2048
	ds_read_b128 v[158:161], v149 offset:3072
	v_add_u32_e32 v149, s54, v145
	ds_read_b128 v[162:165], v149
	ds_read_b128 v[166:169], v149 offset:1024
	ds_read_b128 v[170:173], v149 offset:2048
	ds_read_b128 v[174:177], v149 offset:3072
	v_lshl_add_u64 v[192:193], s[34:35], 0, v[136:137]
	s_add_i32 m0, s18, 0xc000
	ds_read_b128 v[178:181], v148
	ds_read_b128 v[184:187], v148 offset:1024
	ds_read_b128 v[188:191], v148 offset:2048
	ds_read_b128 v[196:199], v148 offset:3072
	ds_read_b128 v[210:213], v148 offset:4096
	ds_read_b128 v[214:217], v148 offset:5120
	ds_read_b128 v[218:221], v148 offset:6144
	ds_read_b128 v[222:225], v148 offset:7168
	global_load_lds_dwordx4 v[192:193], off
	v_lshl_add_u64 v[192:193], s[34:35], 0, v[138:139]
	s_add_i32 m0, s18, 0xe000
	s_nop 0
	global_load_lds_dwordx4 v[192:193], off
	s_waitcnt vmcnt(8)
	s_cmp_lt_u32 s32, 0x100
	s_cbranch_scc1 .Llgk_skip_8
	s_waitcnt lgkmcnt(0)
.Llgk_skip_8:
	s_barrier
	s_waitcnt lgkmcnt(0)
	v_mfma_f32_16x16x32_bf16 v[126:129], v[140:143], v[178:181], v[126:129]
	v_mfma_f32_16x16x32_bf16 v[122:125], v[154:157], v[178:181], v[122:125]
	v_mfma_f32_16x16x32_bf16 v[110:113], v[140:143], v[188:191], v[110:113]
	v_mfma_f32_16x16x32_bf16 v[106:109], v[154:157], v[188:191], v[106:109]
	v_mfma_f32_16x16x32_bf16 v[94:97], v[140:143], v[210:213], v[94:97]
	v_mfma_f32_16x16x32_bf16 v[90:93], v[154:157], v[210:213], v[90:93]
	v_mfma_f32_16x16x32_bf16 v[78:81], v[140:143], v[218:221], v[78:81]
	v_mfma_f32_16x16x32_bf16 v[74:77], v[154:157], v[218:221], v[74:77]
	v_mfma_f32_16x16x32_bf16 v[126:129], v[150:153], v[184:187], v[126:129]
	v_mfma_f32_16x16x32_bf16 v[122:125], v[158:161], v[184:187], v[122:125]
	v_mfma_f32_16x16x32_bf16 v[110:113], v[150:153], v[196:199], v[110:113]
	v_mfma_f32_16x16x32_bf16 v[106:109], v[158:161], v[196:199], v[106:109]
	v_mfma_f32_16x16x32_bf16 v[94:97], v[150:153], v[214:217], v[94:97]
	v_mfma_f32_16x16x32_bf16 v[90:93], v[158:161], v[214:217], v[90:93]
	v_mfma_f32_16x16x32_bf16 v[78:81], v[150:153], v[222:225], v[78:81]
	v_mfma_f32_16x16x32_bf16 v[74:77], v[158:161], v[222:225], v[74:77]
	v_mfma_f32_16x16x32_bf16 v[118:121], v[162:165], v[178:181], v[118:121]
	v_mfma_f32_16x16x32_bf16 v[114:117], v[170:173], v[178:181], v[114:117]
	v_mfma_f32_16x16x32_bf16 v[102:105], v[162:165], v[188:191], v[102:105]
	v_mfma_f32_16x16x32_bf16 v[98:101], v[170:173], v[188:191], v[98:101]
	v_mfma_f32_16x16x32_bf16 v[86:89], v[162:165], v[210:213], v[86:89]
	v_mfma_f32_16x16x32_bf16 v[82:85], v[170:173], v[210:213], v[82:85]
	v_mfma_f32_16x16x32_bf16 v[70:73], v[162:165], v[218:221], v[70:73]
	v_mfma_f32_16x16x32_bf16 v[66:69], v[170:173], v[218:221], v[66:69]
	v_mfma_f32_16x16x32_bf16 v[118:121], v[166:169], v[184:187], v[118:121]
	v_mfma_f32_16x16x32_bf16 v[114:117], v[174:177], v[184:187], v[114:117]
	v_mfma_f32_16x16x32_bf16 v[102:105], v[166:169], v[196:199], v[102:105]
	v_mfma_f32_16x16x32_bf16 v[98:101], v[174:177], v[196:199], v[98:101]
	v_mfma_f32_16x16x32_bf16 v[86:89], v[166:169], v[214:217], v[86:89]
	v_mfma_f32_16x16x32_bf16 v[82:85], v[174:177], v[214:217], v[82:85]
	v_mfma_f32_16x16x32_bf16 v[70:73], v[166:169], v[222:225], v[70:73]
	v_mfma_f32_16x16x32_bf16 v[66:69], v[174:177], v[222:225], v[66:69]
	s_barrier
	s_add_i32 s51, s51, s0
	v_lshl_add_u64 v[192:193], s[36:37], 0, v[0:1]
	s_mov_b32 m0, s51
	ds_read_b128 v[178:181], v148 offset:16384
	ds_read_b128 v[184:187], v148 offset:17408
	ds_read_b128 v[188:191], v148 offset:18432
	ds_read_b128 v[196:199], v148 offset:19456
	ds_read_b128 v[210:213], v148 offset:20480
	ds_read_b128 v[214:217], v148 offset:21504
	ds_read_b128 v[218:221], v148 offset:22528
	ds_read_b128 v[222:225], v148 offset:23552
	global_load_lds_dwordx4 v[192:193], off
	s_add_i32 m0, s51, 0x2000
	s_add_u32 s52, s36, 0x40000
	v_lshl_add_u64 v[202:203], s[36:37], 0, v[130:131]
	s_addc_u32 s53, s37, 0
	s_add_i32 s51, s54, s0
	global_load_lds_dwordx4 v[202:203], off
	v_lshl_add_u64 v[226:227], s[52:53], 0, v[0:1]
	s_mov_b32 m0, s51
	v_lshl_add_u64 v[228:229], s[40:41], 0, v[132:133]
	global_load_lds_dwordx4 v[226:227], off
	v_lshl_add_u64 v[226:227], s[52:53], 0, v[130:131]
	s_add_i32 m0, s51, 0x2000
	s_nop 0
	global_load_lds_dwordx4 v[226:227], off
	v_lshl_add_u64 v[226:227], s[40:41], 0, v[134:135]
	s_mov_b32 m0, s18
	s_nop 0
	global_load_lds_dwordx4 v[226:227], off
	s_mov_b32 m0, s19
	s_nop 0
	global_load_lds_dwordx4 v[228:229], off
	s_waitcnt vmcnt(8)
	s_cmp_lt_u32 s32, 0x100
	s_cbranch_scc1 .Llgk_skip_9
	s_waitcnt lgkmcnt(0)
.Llgk_skip_9:
	s_barrier
	s_waitcnt lgkmcnt(0)
	v_mfma_f32_16x16x32_bf16 v[62:65], v[140:143], v[178:181], v[62:65]
	v_mfma_f32_16x16x32_bf16 v[58:61], v[154:157], v[178:181], v[58:61]
	v_mfma_f32_16x16x32_bf16 v[46:49], v[140:143], v[188:191], v[46:49]
	v_mfma_f32_16x16x32_bf16 v[42:45], v[154:157], v[188:191], v[42:45]
	v_mfma_f32_16x16x32_bf16 v[30:33], v[140:143], v[210:213], v[30:33]
	v_mfma_f32_16x16x32_bf16 v[26:29], v[154:157], v[210:213], v[26:29]
	v_mfma_f32_16x16x32_bf16 v[14:17], v[140:143], v[218:221], v[14:17]
	v_mfma_f32_16x16x32_bf16 v[10:13], v[154:157], v[218:221], v[10:13]
	v_mfma_f32_16x16x32_bf16 v[62:65], v[150:153], v[184:187], v[62:65]
	v_mfma_f32_16x16x32_bf16 v[58:61], v[158:161], v[184:187], v[58:61]
	v_mfma_f32_16x16x32_bf16 v[46:49], v[150:153], v[196:199], v[46:49]
	v_mfma_f32_16x16x32_bf16 v[42:45], v[158:161], v[196:199], v[42:45]
	v_mfma_f32_16x16x32_bf16 v[30:33], v[150:153], v[214:217], v[30:33]
	v_mfma_f32_16x16x32_bf16 v[26:29], v[158:161], v[214:217], v[26:29]
	v_mfma_f32_16x16x32_bf16 v[14:17], v[150:153], v[222:225], v[14:17]
	v_mfma_f32_16x16x32_bf16 v[10:13], v[158:161], v[222:225], v[10:13]
	v_mfma_f32_16x16x32_bf16 v[54:57], v[162:165], v[178:181], v[54:57]
	v_mfma_f32_16x16x32_bf16 v[50:53], v[170:173], v[178:181], v[50:53]
	v_mfma_f32_16x16x32_bf16 v[38:41], v[162:165], v[188:191], v[38:41]
	v_mfma_f32_16x16x32_bf16 v[34:37], v[170:173], v[188:191], v[34:37]
	v_mfma_f32_16x16x32_bf16 v[22:25], v[162:165], v[210:213], v[22:25]
	v_mfma_f32_16x16x32_bf16 v[18:21], v[170:173], v[210:213], v[18:21]
	v_mfma_f32_16x16x32_bf16 v[6:9], v[162:165], v[218:221], v[6:9]
	v_mfma_f32_16x16x32_bf16 v[2:5], v[170:173], v[218:221], v[2:5]
	v_mfma_f32_16x16x32_bf16 v[54:57], v[166:169], v[184:187], v[54:57]
	v_mfma_f32_16x16x32_bf16 v[50:53], v[174:177], v[184:187], v[50:53]
	v_mfma_f32_16x16x32_bf16 v[38:41], v[166:169], v[196:199], v[38:41]
	v_mfma_f32_16x16x32_bf16 v[34:37], v[174:177], v[196:199], v[34:37]
	v_mfma_f32_16x16x32_bf16 v[22:25], v[166:169], v[214:217], v[22:25]
	v_mfma_f32_16x16x32_bf16 v[18:21], v[174:177], v[214:217], v[18:21]
	v_mfma_f32_16x16x32_bf16 v[6:9], v[166:169], v[222:225], v[6:9]
	v_mfma_f32_16x16x32_bf16 v[2:5], v[174:177], v[222:225], v[2:5]
	s_barrier
	s_add_i32 s51, 0, 0x18000
	v_add_u32_e32 v149, s51, v145
	s_add_i32 s52, 0, 0x1c000
	ds_read_b128 v[140:143], v149
	ds_read_b128 v[150:153], v149 offset:1024
	ds_read_b128 v[154:157], v149 offset:2048
	ds_read_b128 v[158:161], v149 offset:3072
	v_add_u32_e32 v149, s52, v145
	ds_read_b128 v[162:165], v149
	ds_read_b128 v[166:169], v149 offset:1024
	ds_read_b128 v[170:173], v149 offset:2048
	ds_read_b128 v[174:177], v149 offset:3072
	s_add_u32 s40, s40, 0x40000
	s_addc_u32 s41, s41, 0
	s_mov_b32 m0, s24
	v_lshl_add_u64 v[230:231], s[40:41], 0, v[134:135]
	ds_read_b128 v[178:181], v148 offset:32768
	ds_read_b128 v[184:187], v148 offset:33792
	ds_read_b128 v[188:191], v148 offset:34816
	ds_read_b128 v[196:199], v148 offset:35840
	ds_read_b128 v[210:213], v148 offset:36864
	ds_read_b128 v[214:217], v148 offset:37888
	ds_read_b128 v[218:221], v148 offset:38912
	ds_read_b128 v[222:225], v148 offset:39936
	global_load_lds_dwordx4 v[230:231], off
	v_lshl_add_u64 v[230:231], s[40:41], 0, v[132:133]
	s_mov_b32 m0, s25
	s_nop 0
	global_load_lds_dwordx4 v[230:231], off
	s_waitcnt vmcnt(8)
	s_cmp_lt_u32 s32, 0x100
	s_cbranch_scc1 .Llgk_skip_10
	s_waitcnt lgkmcnt(0)
.Llgk_skip_10:
	s_barrier
	s_waitcnt lgkmcnt(0)
	v_mfma_f32_16x16x32_bf16 v[126:129], v[140:143], v[178:181], v[126:129]
	v_mfma_f32_16x16x32_bf16 v[122:125], v[154:157], v[178:181], v[122:125]
	v_mfma_f32_16x16x32_bf16 v[110:113], v[140:143], v[188:191], v[110:113]
	v_mfma_f32_16x16x32_bf16 v[106:109], v[154:157], v[188:191], v[106:109]
	v_mfma_f32_16x16x32_bf16 v[94:97], v[140:143], v[210:213], v[94:97]
	v_mfma_f32_16x16x32_bf16 v[90:93], v[154:157], v[210:213], v[90:93]
	v_mfma_f32_16x16x32_bf16 v[78:81], v[140:143], v[218:221], v[78:81]
	v_mfma_f32_16x16x32_bf16 v[74:77], v[154:157], v[218:221], v[74:77]
	v_mfma_f32_16x16x32_bf16 v[126:129], v[150:153], v[184:187], v[126:129]
	v_mfma_f32_16x16x32_bf16 v[122:125], v[158:161], v[184:187], v[122:125]
	v_mfma_f32_16x16x32_bf16 v[110:113], v[150:153], v[196:199], v[110:113]
	v_mfma_f32_16x16x32_bf16 v[106:109], v[158:161], v[196:199], v[106:109]
	v_mfma_f32_16x16x32_bf16 v[94:97], v[150:153], v[214:217], v[94:97]
	v_mfma_f32_16x16x32_bf16 v[90:93], v[158:161], v[214:217], v[90:93]
	v_mfma_f32_16x16x32_bf16 v[78:81], v[150:153], v[222:225], v[78:81]
	v_mfma_f32_16x16x32_bf16 v[74:77], v[158:161], v[222:225], v[74:77]
	v_mfma_f32_16x16x32_bf16 v[118:121], v[162:165], v[178:181], v[118:121]
	v_mfma_f32_16x16x32_bf16 v[114:117], v[170:173], v[178:181], v[114:117]
	v_mfma_f32_16x16x32_bf16 v[102:105], v[162:165], v[188:191], v[102:105]
	v_mfma_f32_16x16x32_bf16 v[98:101], v[170:173], v[188:191], v[98:101]
	v_mfma_f32_16x16x32_bf16 v[86:89], v[162:165], v[210:213], v[86:89]
	v_mfma_f32_16x16x32_bf16 v[82:85], v[170:173], v[210:213], v[82:85]
	v_mfma_f32_16x16x32_bf16 v[70:73], v[162:165], v[218:221], v[70:73]
	v_mfma_f32_16x16x32_bf16 v[66:69], v[170:173], v[218:221], v[66:69]
	v_mfma_f32_16x16x32_bf16 v[118:121], v[166:169], v[184:187], v[118:121]
	v_mfma_f32_16x16x32_bf16 v[114:117], v[174:177], v[184:187], v[114:117]
	v_mfma_f32_16x16x32_bf16 v[102:105], v[166:169], v[196:199], v[102:105]
	v_mfma_f32_16x16x32_bf16 v[98:101], v[174:177], v[196:199], v[98:101]
	v_mfma_f32_16x16x32_bf16 v[86:89], v[166:169], v[214:217], v[86:89]
	v_mfma_f32_16x16x32_bf16 v[82:85], v[174:177], v[214:217], v[82:85]
	v_mfma_f32_16x16x32_bf16 v[70:73], v[166:169], v[222:225], v[70:73]
	v_mfma_f32_16x16x32_bf16 v[66:69], v[174:177], v[222:225], v[66:69]
	s_barrier
	s_add_i32 s40, s51, s0
	v_lshl_add_u64 v[192:193], v[192:193], 0, s[22:23]
	s_mov_b32 m0, s40
	ds_read_b128 v[178:181], v148 offset:49152
	ds_read_b128 v[184:187], v148 offset:50176
	ds_read_b128 v[188:191], v148 offset:51200
	ds_read_b128 v[196:199], v148 offset:52224
	ds_read_b128 v[210:213], v148 offset:53248
	ds_read_b128 v[214:217], v148 offset:54272
	ds_read_b128 v[218:221], v148 offset:55296
	ds_read_b128 v[222:225], v148 offset:56320
	global_load_lds_dwordx4 v[192:193], off
	s_add_i32 m0, s40, 0x2000
	s_add_u32 s36, s36, 0x40080
	v_lshl_add_u64 v[192:193], v[202:203], 0, s[22:23]
	s_addc_u32 s37, s37, 0
	s_add_i32 s40, s52, s0
	global_load_lds_dwordx4 v[192:193], off
	v_lshl_add_u64 v[192:193], s[36:37], 0, v[0:1]
	s_mov_b32 m0, s40
	s_nop 0
	global_load_lds_dwordx4 v[192:193], off
	v_lshl_add_u64 v[192:193], s[36:37], 0, v[130:131]
	s_add_i32 m0, s40, 0x2000
	s_nop 0
	global_load_lds_dwordx4 v[192:193], off
	v_lshl_add_u64 v[192:193], v[226:227], 0, s[22:23]
	s_mov_b32 m0, s26
	s_nop 0
	global_load_lds_dwordx4 v[192:193], off
	v_lshl_add_u64 v[192:193], v[228:229], 0, s[22:23]
	s_mov_b32 m0, s28
	s_nop 0
	global_load_lds_dwordx4 v[192:193], off
	s_waitcnt vmcnt(8)
	s_cmp_lt_u32 s32, 0x100
	s_cbranch_scc1 .Llgk_skip_11
	s_waitcnt lgkmcnt(0)
.Llgk_skip_11:
	s_barrier
	s_waitcnt lgkmcnt(0)
	v_mfma_f32_16x16x32_bf16 v[62:65], v[140:143], v[178:181], v[62:65]
	v_mfma_f32_16x16x32_bf16 v[58:61], v[154:157], v[178:181], v[58:61]
	v_mfma_f32_16x16x32_bf16 v[46:49], v[140:143], v[188:191], v[46:49]
	v_mfma_f32_16x16x32_bf16 v[42:45], v[154:157], v[188:191], v[42:45]
	v_mfma_f32_16x16x32_bf16 v[30:33], v[140:143], v[210:213], v[30:33]
	v_mfma_f32_16x16x32_bf16 v[26:29], v[154:157], v[210:213], v[26:29]
	v_mfma_f32_16x16x32_bf16 v[14:17], v[140:143], v[218:221], v[14:17]
	v_mfma_f32_16x16x32_bf16 v[10:13], v[154:157], v[218:221], v[10:13]
	v_mfma_f32_16x16x32_bf16 v[62:65], v[150:153], v[184:187], v[62:65]
	v_mfma_f32_16x16x32_bf16 v[58:61], v[158:161], v[184:187], v[58:61]
	v_mfma_f32_16x16x32_bf16 v[46:49], v[150:153], v[196:199], v[46:49]
	v_mfma_f32_16x16x32_bf16 v[42:45], v[158:161], v[196:199], v[42:45]
	v_mfma_f32_16x16x32_bf16 v[30:33], v[150:153], v[214:217], v[30:33]
	v_mfma_f32_16x16x32_bf16 v[26:29], v[158:161], v[214:217], v[26:29]
	v_mfma_f32_16x16x32_bf16 v[14:17], v[150:153], v[222:225], v[14:17]
	v_mfma_f32_16x16x32_bf16 v[10:13], v[158:161], v[222:225], v[10:13]
	v_mfma_f32_16x16x32_bf16 v[54:57], v[162:165], v[178:181], v[54:57]
	v_mfma_f32_16x16x32_bf16 v[50:53], v[170:173], v[178:181], v[50:53]
	v_mfma_f32_16x16x32_bf16 v[38:41], v[162:165], v[188:191], v[38:41]
	v_mfma_f32_16x16x32_bf16 v[34:37], v[170:173], v[188:191], v[34:37]
	v_mfma_f32_16x16x32_bf16 v[22:25], v[162:165], v[210:213], v[22:25]
	v_mfma_f32_16x16x32_bf16 v[18:21], v[170:173], v[210:213], v[18:21]
	v_mfma_f32_16x16x32_bf16 v[6:9], v[162:165], v[218:221], v[6:9]
	v_mfma_f32_16x16x32_bf16 v[2:5], v[170:173], v[218:221], v[2:5]
	v_mfma_f32_16x16x32_bf16 v[54:57], v[166:169], v[184:187], v[54:57]
	v_mfma_f32_16x16x32_bf16 v[50:53], v[174:177], v[184:187], v[50:53]
	v_mfma_f32_16x16x32_bf16 v[38:41], v[166:169], v[196:199], v[38:41]
	v_mfma_f32_16x16x32_bf16 v[34:37], v[174:177], v[196:199], v[34:37]
	v_mfma_f32_16x16x32_bf16 v[22:25], v[166:169], v[214:217], v[22:25]
	v_mfma_f32_16x16x32_bf16 v[18:21], v[174:177], v[214:217], v[18:21]
	v_mfma_f32_16x16x32_bf16 v[6:9], v[166:169], v[222:225], v[6:9]
	v_mfma_f32_16x16x32_bf16 v[2:5], v[174:177], v[222:225], v[2:5]
	s_barrier
	s_add_i32 s50, s50, 2
	s_add_u32 s34, s34, 0x100
	s_addc_u32 s35, s35, 0
	s_add_u32 s48, s48, 0x100
	s_addc_u32 s49, s49, 0
	s_cmp_gt_u32 s50, 13
	s_cbranch_scc0 .LBB0_792
	s_setprio 0
	s_and_b64 vcc, exec, s[10:11]
	s_cbranch_vccz .LBB0_795
	s_barrier

.Lsprio_3:
.LBB0_864:
	s_add_u32 s30, s12, 0xfff00080
	s_addc_u32 s31, s13, -1
	s_add_i32 s45, 0, 0x10000
	s_cmp_eq_u32 s35, 60
	s_cselect_b32 s37, s3, s31
	s_cselect_b32 s36, s16, s30
	s_cselect_b32 s31, s24, s28
	s_cselect_b32 s30, s25, s26
	s_add_i32 s59, 0, 0x14000
	v_add_u32_e32 v156, s45, v145
	v_add_u32_e32 v172, s59, v145
	ds_read_b128 v[140:143], v156
	ds_read_b128 v[148:151], v156 offset:1024
	ds_read_b128 v[152:155], v156 offset:2048
	ds_read_b128 v[156:159], v156 offset:3072
	ds_read_b128 v[160:163], v172
	ds_read_b128 v[164:167], v172 offset:1024
	ds_read_b128 v[168:171], v172 offset:2048
	ds_read_b128 v[172:175], v172 offset:3072
	v_lshl_add_u64 v[180:181], s[12:13], 0, v[136:137]
	s_add_i32 m0, s51, 0xc000
	ds_read_b128 v[176:179], v147
	ds_read_b128 v[184:187], v147 offset:1024
	ds_read_b128 v[188:191], v147 offset:2048
	ds_read_b128 v[196:199], v147 offset:3072
	ds_read_b128 v[210:213], v147 offset:4096
	ds_read_b128 v[214:217], v147 offset:5120
	ds_read_b128 v[218:221], v147 offset:6144
	ds_read_b128 v[222:225], v147 offset:7168
	global_load_lds_dwordx4 v[180:181], off
	v_lshl_add_u64 v[180:181], s[12:13], 0, v[138:139]
	s_add_i32 m0, s51, 0xe000
	s_nop 0
	global_load_lds_dwordx4 v[180:181], off
	s_waitcnt vmcnt(8)
	s_cmp_lt_u32 s32, 0x100
	s_cbranch_scc1 .Llgk_skip_12
	s_waitcnt lgkmcnt(0)
.Llgk_skip_12:
	s_barrier
	s_waitcnt lgkmcnt(0)
	v_mfma_f32_16x16x32_bf16 v[126:129], v[140:143], v[176:179], v[126:129]
	v_mfma_f32_16x16x32_bf16 v[122:125], v[152:155], v[176:179], v[122:125]
	v_mfma_f32_16x16x32_bf16 v[110:113], v[140:143], v[188:191], v[110:113]
	v_mfma_f32_16x16x32_bf16 v[106:109], v[152:155], v[188:191], v[106:109]
	v_mfma_f32_16x16x32_bf16 v[94:97], v[140:143], v[210:213], v[94:97]
	v_mfma_f32_16x16x32_bf16 v[90:93], v[152:155], v[210:213], v[90:93]
	v_mfma_f32_16x16x32_bf16 v[78:81], v[140:143], v[218:221], v[78:81]
	v_mfma_f32_16x16x32_bf16 v[74:77], v[152:155], v[218:221], v[74:77]
	v_mfma_f32_16x16x32_bf16 v[126:129], v[148:151], v[184:187], v[126:129]
	v_mfma_f32_16x16x32_bf16 v[122:125], v[156:159], v[184:187], v[122:125]
	v_mfma_f32_16x16x32_bf16 v[110:113], v[148:151], v[196:199], v[110:113]
	v_mfma_f32_16x16x32_bf16 v[106:109], v[156:159], v[196:199], v[106:109]
	v_mfma_f32_16x16x32_bf16 v[94:97], v[148:151], v[214:217], v[94:97]
	v_mfma_f32_16x16x32_bf16 v[90:93], v[156:159], v[214:217], v[90:93]
	v_mfma_f32_16x16x32_bf16 v[78:81], v[148:151], v[222:225], v[78:81]
	v_mfma_f32_16x16x32_bf16 v[74:77], v[156:159], v[222:225], v[74:77]
	v_mfma_f32_16x16x32_bf16 v[118:121], v[160:163], v[176:179], v[118:121]
	v_mfma_f32_16x16x32_bf16 v[114:117], v[168:171], v[176:179], v[114:117]
	v_mfma_f32_16x16x32_bf16 v[102:105], v[160:163], v[188:191], v[102:105]
	v_mfma_f32_16x16x32_bf16 v[98:101], v[168:171], v[188:191], v[98:101]
	v_mfma_f32_16x16x32_bf16 v[86:89], v[160:163], v[210:213], v[86:89]
	v_mfma_f32_16x16x32_bf16 v[82:85], v[168:171], v[210:213], v[82:85]
	v_mfma_f32_16x16x32_bf16 v[70:73], v[160:163], v[218:221], v[70:73]
	v_mfma_f32_16x16x32_bf16 v[66:69], v[168:171], v[218:221], v[66:69]
	v_mfma_f32_16x16x32_bf16 v[118:121], v[164:167], v[184:187], v[118:121]
	v_mfma_f32_16x16x32_bf16 v[114:117], v[172:175], v[184:187], v[114:117]
	v_mfma_f32_16x16x32_bf16 v[102:105], v[164:167], v[196:199], v[102:105]
	v_mfma_f32_16x16x32_bf16 v[98:101], v[172:175], v[196:199], v[98:101]
	v_mfma_f32_16x16x32_bf16 v[86:89], v[164:167], v[214:217], v[86:89]
	v_mfma_f32_16x16x32_bf16 v[82:85], v[172:175], v[214:217], v[82:85]
	v_mfma_f32_16x16x32_bf16 v[70:73], v[164:167], v[222:225], v[70:73]
	v_mfma_f32_16x16x32_bf16 v[66:69], v[172:175], v[222:225], v[66:69]
	s_barrier
	s_add_i32 s45, s45, s50
	v_lshl_add_u64 v[180:181], s[30:31], 0, v[0:1]
	s_mov_b32 m0, s45
	ds_read_b128 v[176:179], v147 offset:16384
	ds_read_b128 v[184:187], v147 offset:17408
	ds_read_b128 v[188:191], v147 offset:18432
	ds_read_b128 v[196:199], v147 offset:19456
	ds_read_b128 v[210:213], v147 offset:20480
	ds_read_b128 v[214:217], v147 offset:21504
	ds_read_b128 v[218:221], v147 offset:22528
	ds_read_b128 v[222:225], v147 offset:23552
	global_load_lds_dwordx4 v[180:181], off
	s_add_i32 m0, s45, 0x2000
	s_add_u32 s60, s30, 0x100000
	v_lshl_add_u64 v[192:193], s[30:31], 0, v[130:131]
	s_addc_u32 s61, s31, 0
	s_add_i32 s45, s59, s50
	global_load_lds_dwordx4 v[192:193], off
	v_lshl_add_u64 v[202:203], s[60:61], 0, v[0:1]
	s_mov_b32 m0, s45
	v_lshl_add_u64 v[226:227], s[36:37], 0, v[132:133]
	global_load_lds_dwordx4 v[202:203], off
	v_lshl_add_u64 v[202:203], s[60:61], 0, v[130:131]
	s_add_i32 m0, s45, 0x2000
	s_nop 0
	global_load_lds_dwordx4 v[202:203], off
	v_lshl_add_u64 v[202:203], s[36:37], 0, v[134:135]
	s_mov_b32 m0, s51
	s_nop 0
	global_load_lds_dwordx4 v[202:203], off
	s_mov_b32 m0, s52
	s_nop 0
	global_load_lds_dwordx4 v[226:227], off
	s_waitcnt vmcnt(8)
	s_cmp_lt_u32 s32, 0x100
	s_cbranch_scc1 .Llgk_skip_13
	s_waitcnt lgkmcnt(0)
.Llgk_skip_13:
	s_barrier
	s_waitcnt lgkmcnt(0)
	v_mfma_f32_16x16x32_bf16 v[62:65], v[140:143], v[176:179], v[62:65]
	v_mfma_f32_16x16x32_bf16 v[58:61], v[152:155], v[176:179], v[58:61]
	v_mfma_f32_16x16x32_bf16 v[46:49], v[140:143], v[188:191], v[46:49]
	v_mfma_f32_16x16x32_bf16 v[42:45], v[152:155], v[188:191], v[42:45]
	v_mfma_f32_16x16x32_bf16 v[30:33], v[140:143], v[210:213], v[30:33]
	v_mfma_f32_16x16x32_bf16 v[26:29], v[152:155], v[210:213], v[26:29]
	v_mfma_f32_16x16x32_bf16 v[14:17], v[140:143], v[218:221], v[14:17]
	v_mfma_f32_16x16x32_bf16 v[10:13], v[152:155], v[218:221], v[10:13]
	v_mfma_f32_16x16x32_bf16 v[62:65], v[148:151], v[184:187], v[62:65]
	v_mfma_f32_16x16x32_bf16 v[58:61], v[156:159], v[184:187], v[58:61]
	v_mfma_f32_16x16x32_bf16 v[46:49], v[148:151], v[196:199], v[46:49]
	v_mfma_f32_16x16x32_bf16 v[42:45], v[156:159], v[196:199], v[42:45]
	v_mfma_f32_16x16x32_bf16 v[30:33], v[148:151], v[214:217], v[30:33]
	v_mfma_f32_16x16x32_bf16 v[26:29], v[156:159], v[214:217], v[26:29]
	v_mfma_f32_16x16x32_bf16 v[14:17], v[148:151], v[222:225], v[14:17]
	v_mfma_f32_16x16x32_bf16 v[10:13], v[156:159], v[222:225], v[10:13]
	v_mfma_f32_16x16x32_bf16 v[54:57], v[160:163], v[176:179], v[54:57]
	v_mfma_f32_16x16x32_bf16 v[50:53], v[168:171], v[176:179], v[50:53]
	v_mfma_f32_16x16x32_bf16 v[38:41], v[160:163], v[188:191], v[38:41]
	v_mfma_f32_16x16x32_bf16 v[34:37], v[168:171], v[188:191], v[34:37]
	v_mfma_f32_16x16x32_bf16 v[22:25], v[160:163], v[210:213], v[22:25]
	v_mfma_f32_16x16x32_bf16 v[18:21], v[168:171], v[210:213], v[18:21]
	v_mfma_f32_16x16x32_bf16 v[6:9], v[160:163], v[218:221], v[6:9]
	v_mfma_f32_16x16x32_bf16 v[2:5], v[168:171], v[218:221], v[2:5]
	v_mfma_f32_16x16x32_bf16 v[54:57], v[164:167], v[184:187], v[54:57]
	v_mfma_f32_16x16x32_bf16 v[50:53], v[172:175], v[184:187], v[50:53]
	v_mfma_f32_16x16x32_bf16 v[38:41], v[164:167], v[196:199], v[38:41]
	v_mfma_f32_16x16x32_bf16 v[34:37], v[172:175], v[196:199], v[34:37]
	v_mfma_f32_16x16x32_bf16 v[22:25], v[164:167], v[214:217], v[22:25]
	v_mfma_f32_16x16x32_bf16 v[18:21], v[172:175], v[214:217], v[18:21]
	v_mfma_f32_16x16x32_bf16 v[6:9], v[164:167], v[222:225], v[6:9]
	v_mfma_f32_16x16x32_bf16 v[2:5], v[172:175], v[222:225], v[2:5]
	s_barrier
	s_add_i32 s45, 0, 0x18000
	s_add_i32 s59, 0, 0x1c000
	v_add_u32_e32 v156, s45, v145
	v_add_u32_e32 v172, s59, v145
	ds_read_b128 v[140:143], v156
	ds_read_b128 v[148:151], v156 offset:1024
	ds_read_b128 v[152:155], v156 offset:2048
	ds_read_b128 v[156:159], v156 offset:3072
	ds_read_b128 v[160:163], v172
	ds_read_b128 v[164:167], v172 offset:1024
	ds_read_b128 v[168:171], v172 offset:2048
	ds_read_b128 v[172:175], v172 offset:3072
	s_add_u32 s36, s36, 0x100000
	s_addc_u32 s37, s37, 0
	s_mov_b32 m0, s53
	v_lshl_add_u64 v[228:229], s[36:37], 0, v[134:135]
	ds_read_b128 v[176:179], v147 offset:32768
	ds_read_b128 v[184:187], v147 offset:33792
	ds_read_b128 v[188:191], v147 offset:34816
	ds_read_b128 v[196:199], v147 offset:35840
	ds_read_b128 v[210:213], v147 offset:36864
	ds_read_b128 v[214:217], v147 offset:37888
	ds_read_b128 v[218:221], v147 offset:38912
	ds_read_b128 v[222:225], v147 offset:39936
	global_load_lds_dwordx4 v[228:229], off
	v_lshl_add_u64 v[228:229], s[36:37], 0, v[132:133]
	s_mov_b32 m0, s54
	s_nop 0
	global_load_lds_dwordx4 v[228:229], off
	s_waitcnt vmcnt(8)
	s_cmp_lt_u32 s32, 0x100
	s_cbranch_scc1 .Llgk_skip_14
	s_waitcnt lgkmcnt(0)
.Llgk_skip_14:
	s_barrier
	s_waitcnt lgkmcnt(0)
	v_mfma_f32_16x16x32_bf16 v[126:129], v[140:143], v[176:179], v[126:129]
	v_mfma_f32_16x16x32_bf16 v[122:125], v[152:155], v[176:179], v[122:125]
	v_mfma_f32_16x16x32_bf16 v[110:113], v[140:143], v[188:191], v[110:113]
	v_mfma_f32_16x16x32_bf16 v[106:109], v[152:155], v[188:191], v[106:109]
	v_mfma_f32_16x16x32_bf16 v[94:97], v[140:143], v[210:213], v[94:97]
	v_mfma_f32_16x16x32_bf16 v[90:93], v[152:155], v[210:213], v[90:93]
	v_mfma_f32_16x16x32_bf16 v[78:81], v[140:143], v[218:221], v[78:81]
	v_mfma_f32_16x16x32_bf16 v[74:77], v[152:155], v[218:221], v[74:77]
	v_mfma_f32_16x16x32_bf16 v[126:129], v[148:151], v[184:187], v[126:129]
	v_mfma_f32_16x16x32_bf16 v[122:125], v[156:159], v[184:187], v[122:125]
	v_mfma_f32_16x16x32_bf16 v[110:113], v[148:151], v[196:199], v[110:113]
	v_mfma_f32_16x16x32_bf16 v[106:109], v[156:159], v[196:199], v[106:109]
	v_mfma_f32_16x16x32_bf16 v[94:97], v[148:151], v[214:217], v[94:97]
	v_mfma_f32_16x16x32_bf16 v[90:93], v[156:159], v[214:217], v[90:93]
	v_mfma_f32_16x16x32_bf16 v[78:81], v[148:151], v[222:225], v[78:81]
	v_mfma_f32_16x16x32_bf16 v[74:77], v[156:159], v[222:225], v[74:77]
	v_mfma_f32_16x16x32_bf16 v[118:121], v[160:163], v[176:179], v[118:121]
	v_mfma_f32_16x16x32_bf16 v[114:117], v[168:171], v[176:179], v[114:117]
	v_mfma_f32_16x16x32_bf16 v[102:105], v[160:163], v[188:191], v[102:105]
	v_mfma_f32_16x16x32_bf16 v[98:101], v[168:171], v[188:191], v[98:101]
	v_mfma_f32_16x16x32_bf16 v[86:89], v[160:163], v[210:213], v[86:89]
	v_mfma_f32_16x16x32_bf16 v[82:85], v[168:171], v[210:213], v[82:85]
	v_mfma_f32_16x16x32_bf16 v[70:73], v[160:163], v[218:221], v[70:73]
	v_mfma_f32_16x16x32_bf16 v[66:69], v[168:171], v[218:221], v[66:69]
	v_mfma_f32_16x16x32_bf16 v[118:121], v[164:167], v[184:187], v[118:121]
	v_mfma_f32_16x16x32_bf16 v[114:117], v[172:175], v[184:187], v[114:117]
	v_mfma_f32_16x16x32_bf16 v[102:105], v[164:167], v[196:199], v[102:105]
	v_mfma_f32_16x16x32_bf16 v[98:101], v[172:175], v[196:199], v[98:101]
	v_mfma_f32_16x16x32_bf16 v[86:89], v[164:167], v[214:217], v[86:89]
	v_mfma_f32_16x16x32_bf16 v[82:85], v[172:175], v[214:217], v[82:85]
	v_mfma_f32_16x16x32_bf16 v[70:73], v[164:167], v[222:225], v[70:73]
	v_mfma_f32_16x16x32_bf16 v[66:69], v[172:175], v[222:225], v[66:69]
	s_barrier
	s_add_i32 s36, s45, s50
	v_lshl_add_u64 v[180:181], v[180:181], 0, s[22:23]
	s_mov_b32 m0, s36
	ds_read_b128 v[176:179], v147 offset:49152
	ds_read_b128 v[184:187], v147 offset:50176
	ds_read_b128 v[188:191], v147 offset:51200
	ds_read_b128 v[196:199], v147 offset:52224
	ds_read_b128 v[210:213], v147 offset:53248
	ds_read_b128 v[214:217], v147 offset:54272
	ds_read_b128 v[218:221], v147 offset:55296
	ds_read_b128 v[222:225], v147 offset:56320
	global_load_lds_dwordx4 v[180:181], off
	s_add_i32 m0, s36, 0x2000
	s_add_u32 s30, s30, 0x100080
	v_lshl_add_u64 v[180:181], v[192:193], 0, s[22:23]
	s_addc_u32 s31, s31, 0
	s_add_i32 s36, s59, s50
	global_load_lds_dwordx4 v[180:181], off
	v_lshl_add_u64 v[180:181], s[30:31], 0, v[0:1]
	s_mov_b32 m0, s36
	s_nop 0
	global_load_lds_dwordx4 v[180:181], off
	v_lshl_add_u64 v[180:181], s[30:31], 0, v[130:131]
	s_add_i32 m0, s36, 0x2000
	s_nop 0
	global_load_lds_dwordx4 v[180:181], off
	v_lshl_add_u64 v[180:181], v[202:203], 0, s[22:23]
	s_mov_b32 m0, s56
	s_nop 0
	global_load_lds_dwordx4 v[180:181], off
	v_lshl_add_u64 v[180:181], v[226:227], 0, s[22:23]
	s_mov_b32 m0, s57
	s_nop 0
	global_load_lds_dwordx4 v[180:181], off
	s_waitcnt vmcnt(8)
	s_cmp_lt_u32 s32, 0x100
	s_cbranch_scc1 .Llgk_skip_15
	s_waitcnt lgkmcnt(0)
.Llgk_skip_15:
	s_barrier
	s_waitcnt lgkmcnt(0)
	v_mfma_f32_16x16x32_bf16 v[62:65], v[140:143], v[176:179], v[62:65]
	v_mfma_f32_16x16x32_bf16 v[58:61], v[152:155], v[176:179], v[58:61]
	v_mfma_f32_16x16x32_bf16 v[46:49], v[140:143], v[188:191], v[46:49]
	v_mfma_f32_16x16x32_bf16 v[42:45], v[152:155], v[188:191], v[42:45]
	v_mfma_f32_16x16x32_bf16 v[30:33], v[140:143], v[210:213], v[30:33]
	v_mfma_f32_16x16x32_bf16 v[26:29], v[152:155], v[210:213], v[26:29]
	v_mfma_f32_16x16x32_bf16 v[14:17], v[140:143], v[218:221], v[14:17]
	v_mfma_f32_16x16x32_bf16 v[10:13], v[152:155], v[218:221], v[10:13]
	v_mfma_f32_16x16x32_bf16 v[62:65], v[148:151], v[184:187], v[62:65]
	v_mfma_f32_16x16x32_bf16 v[58:61], v[156:159], v[184:187], v[58:61]
	v_mfma_f32_16x16x32_bf16 v[46:49], v[148:151], v[196:199], v[46:49]
	v_mfma_f32_16x16x32_bf16 v[42:45], v[156:159], v[196:199], v[42:45]
	v_mfma_f32_16x16x32_bf16 v[30:33], v[148:151], v[214:217], v[30:33]
	v_mfma_f32_16x16x32_bf16 v[26:29], v[156:159], v[214:217], v[26:29]
	v_mfma_f32_16x16x32_bf16 v[14:17], v[148:151], v[222:225], v[14:17]
	v_mfma_f32_16x16x32_bf16 v[10:13], v[156:159], v[222:225], v[10:13]
	v_mfma_f32_16x16x32_bf16 v[54:57], v[160:163], v[176:179], v[54:57]
	v_mfma_f32_16x16x32_bf16 v[50:53], v[168:171], v[176:179], v[50:53]
	v_mfma_f32_16x16x32_bf16 v[38:41], v[160:163], v[188:191], v[38:41]
	v_mfma_f32_16x16x32_bf16 v[34:37], v[168:171], v[188:191], v[34:37]
	v_mfma_f32_16x16x32_bf16 v[22:25], v[160:163], v[210:213], v[22:25]
	v_mfma_f32_16x16x32_bf16 v[18:21], v[168:171], v[210:213], v[18:21]
	v_mfma_f32_16x16x32_bf16 v[6:9], v[160:163], v[218:221], v[6:9]
	v_mfma_f32_16x16x32_bf16 v[2:5], v[168:171], v[218:221], v[2:5]
	v_mfma_f32_16x16x32_bf16 v[54:57], v[164:167], v[184:187], v[54:57]
	v_mfma_f32_16x16x32_bf16 v[50:53], v[172:175], v[184:187], v[50:53]
	v_mfma_f32_16x16x32_bf16 v[38:41], v[164:167], v[196:199], v[38:41]
	v_mfma_f32_16x16x32_bf16 v[34:37], v[172:175], v[196:199], v[34:37]
	v_mfma_f32_16x16x32_bf16 v[22:25], v[164:167], v[214:217], v[22:25]
	v_mfma_f32_16x16x32_bf16 v[18:21], v[172:175], v[214:217], v[18:21]
	v_mfma_f32_16x16x32_bf16 v[6:9], v[164:167], v[222:225], v[6:9]
	v_mfma_f32_16x16x32_bf16 v[2:5], v[172:175], v[222:225], v[2:5]
	s_barrier
	s_add_i32 s35, s35, 2
	s_add_u32 s12, s12, 0x100
	s_addc_u32 s13, s13, 0
	s_add_u32 s26, s26, 0x100
	s_addc_u32 s28, s28, 0
	s_cmp_gt_u32 s35, 61
	s_cbranch_scc0 .LBB0_864
	s_setprio 0
	s_and_b64 vcc, exec, s[20:21]
	s_cbranch_vccz .LBB0_867
	s_barrier

.Lsprio_4:
.LBB0_957:
	s_add_i32 s52, s40, 2
	s_add_u32 s53, s36, 0x80
	s_addc_u32 s41, s37, 0
	s_add_i32 s56, 0, 0x10000
	s_cmp_eq_u32 s44, s40
	s_cselect_b32 s41, s7, s41
	s_cselect_b32 s40, s6, s53
	s_cselect_b32 s55, s35, s51
	s_cselect_b32 s54, s34, s50
	s_add_i32 s53, 0, 0x14000
	v_add_u32_e32 v154, s56, v140
	v_add_u32_e32 v170, s53, v140
	ds_read_b128 v[142:145], v154
	ds_read_b128 v[146:149], v154 offset:1024
	ds_read_b128 v[150:153], v154 offset:2048
	ds_read_b128 v[154:157], v154 offset:3072
	ds_read_b128 v[158:161], v170
	ds_read_b128 v[162:165], v170 offset:1024
	ds_read_b128 v[166:169], v170 offset:2048
	ds_read_b128 v[170:173], v170 offset:3072
	v_lshl_add_u64 v[192:193], s[36:37], 0, v[136:137]
	s_add_i32 m0, s18, 0xc000
	ds_read_b128 v[174:177], v141
	ds_read_b128 v[178:181], v141 offset:1024
	ds_read_b128 v[184:187], v141 offset:2048
	ds_read_b128 v[188:191], v141 offset:3072
	ds_read_b128 v[196:199], v141 offset:4096
	ds_read_b128 v[210:213], v141 offset:5120
	ds_read_b128 v[214:217], v141 offset:6144
	ds_read_b128 v[218:221], v141 offset:7168
	global_load_lds_dwordx4 v[192:193], off
	v_lshl_add_u64 v[192:193], s[36:37], 0, v[138:139]
	s_add_i32 m0, s18, 0xe000
	s_nop 0
	global_load_lds_dwordx4 v[192:193], off
	s_waitcnt vmcnt(8)
	s_cmp_lt_u32 s32, 0x100
	s_cbranch_scc1 .Llgk_skip_16
	s_waitcnt lgkmcnt(0)
.Llgk_skip_16:
	s_barrier
	s_waitcnt lgkmcnt(0)
	v_mfma_f32_16x16x32_bf16 v[122:125], v[142:145], v[174:177], v[122:125]
	v_mfma_f32_16x16x32_bf16 v[126:129], v[150:153], v[174:177], v[126:129]
	v_mfma_f32_16x16x32_bf16 v[110:113], v[142:145], v[184:187], v[110:113]
	v_mfma_f32_16x16x32_bf16 v[106:109], v[150:153], v[184:187], v[106:109]
	v_mfma_f32_16x16x32_bf16 v[94:97], v[142:145], v[196:199], v[94:97]
	v_mfma_f32_16x16x32_bf16 v[90:93], v[150:153], v[196:199], v[90:93]
	v_mfma_f32_16x16x32_bf16 v[78:81], v[142:145], v[214:217], v[78:81]
	v_mfma_f32_16x16x32_bf16 v[74:77], v[150:153], v[214:217], v[74:77]
	v_mfma_f32_16x16x32_bf16 v[122:125], v[146:149], v[178:181], v[122:125]
	v_mfma_f32_16x16x32_bf16 v[126:129], v[154:157], v[178:181], v[126:129]
	v_mfma_f32_16x16x32_bf16 v[110:113], v[146:149], v[188:191], v[110:113]
	v_mfma_f32_16x16x32_bf16 v[106:109], v[154:157], v[188:191], v[106:109]
	v_mfma_f32_16x16x32_bf16 v[94:97], v[146:149], v[210:213], v[94:97]
	v_mfma_f32_16x16x32_bf16 v[90:93], v[154:157], v[210:213], v[90:93]
	v_mfma_f32_16x16x32_bf16 v[78:81], v[146:149], v[218:221], v[78:81]
	v_mfma_f32_16x16x32_bf16 v[74:77], v[154:157], v[218:221], v[74:77]
	v_mfma_f32_16x16x32_bf16 v[118:121], v[158:161], v[174:177], v[118:121]
	v_mfma_f32_16x16x32_bf16 v[114:117], v[166:169], v[174:177], v[114:117]
	v_mfma_f32_16x16x32_bf16 v[102:105], v[158:161], v[184:187], v[102:105]
	v_mfma_f32_16x16x32_bf16 v[98:101], v[166:169], v[184:187], v[98:101]
	v_mfma_f32_16x16x32_bf16 v[86:89], v[158:161], v[196:199], v[86:89]
	v_mfma_f32_16x16x32_bf16 v[82:85], v[166:169], v[196:199], v[82:85]
	v_mfma_f32_16x16x32_bf16 v[70:73], v[158:161], v[214:217], v[70:73]
	v_mfma_f32_16x16x32_bf16 v[66:69], v[166:169], v[214:217], v[66:69]
	v_mfma_f32_16x16x32_bf16 v[118:121], v[162:165], v[178:181], v[118:121]
	v_mfma_f32_16x16x32_bf16 v[114:117], v[170:173], v[178:181], v[114:117]
	v_mfma_f32_16x16x32_bf16 v[102:105], v[162:165], v[188:191], v[102:105]
	v_mfma_f32_16x16x32_bf16 v[98:101], v[170:173], v[188:191], v[98:101]
	v_mfma_f32_16x16x32_bf16 v[86:89], v[162:165], v[210:213], v[86:89]
	v_mfma_f32_16x16x32_bf16 v[82:85], v[170:173], v[210:213], v[82:85]
	v_mfma_f32_16x16x32_bf16 v[70:73], v[162:165], v[218:221], v[70:73]
	v_mfma_f32_16x16x32_bf16 v[66:69], v[170:173], v[218:221], v[66:69]
	s_barrier
	s_add_i32 s56, s56, s17
	v_lshl_add_u64 v[192:193], s[54:55], 0, v[0:1]
	s_mov_b32 m0, s56
	ds_read_b128 v[174:177], v141 offset:16384
	ds_read_b128 v[178:181], v141 offset:17408
	ds_read_b128 v[184:187], v141 offset:18432
	ds_read_b128 v[188:191], v141 offset:19456
	ds_read_b128 v[196:199], v141 offset:20480
	ds_read_b128 v[210:213], v141 offset:21504
	ds_read_b128 v[214:217], v141 offset:22528
	ds_read_b128 v[218:221], v141 offset:23552
	global_load_lds_dwordx4 v[192:193], off
	s_add_i32 m0, s56, 0x2000
	v_lshl_add_u64 v[202:203], s[54:55], 0, v[130:131]
	s_add_u32 s54, s54, s10
	s_addc_u32 s55, s55, s11
	s_add_i32 s53, s53, s17
	global_load_lds_dwordx4 v[202:203], off
	v_lshl_add_u64 v[222:223], s[54:55], 0, v[0:1]
	s_mov_b32 m0, s53
	v_lshl_add_u64 v[224:225], s[54:55], 0, v[130:131]
	global_load_lds_dwordx4 v[222:223], off
	s_add_i32 m0, s53, 0x2000
	v_lshl_add_u64 v[226:227], s[40:41], 0, v[134:135]
	global_load_lds_dwordx4 v[224:225], off
	s_mov_b32 m0, s18
	v_lshl_add_u64 v[228:229], s[40:41], 0, v[132:133]
	global_load_lds_dwordx4 v[226:227], off
	s_mov_b32 m0, s19
	s_nop 0
	global_load_lds_dwordx4 v[228:229], off
	s_waitcnt vmcnt(8)
	s_cmp_lt_u32 s32, 0x100
	s_cbranch_scc1 .Llgk_skip_17
	s_waitcnt lgkmcnt(0)
.Llgk_skip_17:
	s_barrier
	s_waitcnt lgkmcnt(0)
	v_mfma_f32_16x16x32_bf16 v[62:65], v[142:145], v[174:177], v[62:65]
	v_mfma_f32_16x16x32_bf16 v[58:61], v[150:153], v[174:177], v[58:61]
	v_mfma_f32_16x16x32_bf16 v[46:49], v[142:145], v[184:187], v[46:49]
	v_mfma_f32_16x16x32_bf16 v[42:45], v[150:153], v[184:187], v[42:45]
	v_mfma_f32_16x16x32_bf16 v[30:33], v[142:145], v[196:199], v[30:33]
	v_mfma_f32_16x16x32_bf16 v[26:29], v[150:153], v[196:199], v[26:29]
	v_mfma_f32_16x16x32_bf16 v[14:17], v[142:145], v[214:217], v[14:17]
	v_mfma_f32_16x16x32_bf16 v[10:13], v[150:153], v[214:217], v[10:13]
	v_mfma_f32_16x16x32_bf16 v[62:65], v[146:149], v[178:181], v[62:65]
	v_mfma_f32_16x16x32_bf16 v[58:61], v[154:157], v[178:181], v[58:61]
	v_mfma_f32_16x16x32_bf16 v[46:49], v[146:149], v[188:191], v[46:49]
	v_mfma_f32_16x16x32_bf16 v[42:45], v[154:157], v[188:191], v[42:45]
	v_mfma_f32_16x16x32_bf16 v[30:33], v[146:149], v[210:213], v[30:33]
	v_mfma_f32_16x16x32_bf16 v[26:29], v[154:157], v[210:213], v[26:29]
	v_mfma_f32_16x16x32_bf16 v[14:17], v[146:149], v[218:221], v[14:17]
	v_mfma_f32_16x16x32_bf16 v[10:13], v[154:157], v[218:221], v[10:13]
	v_mfma_f32_16x16x32_bf16 v[54:57], v[158:161], v[174:177], v[54:57]
	v_mfma_f32_16x16x32_bf16 v[50:53], v[166:169], v[174:177], v[50:53]
	v_mfma_f32_16x16x32_bf16 v[38:41], v[158:161], v[184:187], v[38:41]
	v_mfma_f32_16x16x32_bf16 v[34:37], v[166:169], v[184:187], v[34:37]
	v_mfma_f32_16x16x32_bf16 v[22:25], v[158:161], v[196:199], v[22:25]
	v_mfma_f32_16x16x32_bf16 v[18:21], v[166:169], v[196:199], v[18:21]
	v_mfma_f32_16x16x32_bf16 v[6:9], v[158:161], v[214:217], v[6:9]
	v_mfma_f32_16x16x32_bf16 v[2:5], v[166:169], v[214:217], v[2:5]
	v_mfma_f32_16x16x32_bf16 v[54:57], v[162:165], v[178:181], v[54:57]
	v_mfma_f32_16x16x32_bf16 v[50:53], v[170:173], v[178:181], v[50:53]
	v_mfma_f32_16x16x32_bf16 v[38:41], v[162:165], v[188:191], v[38:41]
	v_mfma_f32_16x16x32_bf16 v[34:37], v[170:173], v[188:191], v[34:37]
	v_mfma_f32_16x16x32_bf16 v[22:25], v[162:165], v[210:213], v[22:25]
	v_mfma_f32_16x16x32_bf16 v[18:21], v[170:173], v[210:213], v[18:21]
	v_mfma_f32_16x16x32_bf16 v[6:9], v[162:165], v[218:221], v[6:9]
	v_mfma_f32_16x16x32_bf16 v[2:5], v[170:173], v[218:221], v[2:5]
	s_barrier
	s_add_i32 s53, 0, 0x18000
	s_add_i32 s54, 0, 0x1c000
	v_add_u32_e32 v154, s53, v140
	v_add_u32_e32 v170, s54, v140
	ds_read_b128 v[142:145], v154
	ds_read_b128 v[146:149], v154 offset:1024
	ds_read_b128 v[150:153], v154 offset:2048
	ds_read_b128 v[154:157], v154 offset:3072
	ds_read_b128 v[158:161], v170
	ds_read_b128 v[162:165], v170 offset:1024
	ds_read_b128 v[166:169], v170 offset:2048
	ds_read_b128 v[170:173], v170 offset:3072
	s_add_u32 s40, s40, s10
	s_addc_u32 s41, s41, s11
	s_mov_b32 m0, s24
	v_lshl_add_u64 v[230:231], s[40:41], 0, v[134:135]
	ds_read_b128 v[174:177], v141 offset:32768
	ds_read_b128 v[178:181], v141 offset:33792
	ds_read_b128 v[184:187], v141 offset:34816
	ds_read_b128 v[188:191], v141 offset:35840
	ds_read_b128 v[196:199], v141 offset:36864
	ds_read_b128 v[210:213], v141 offset:37888
	ds_read_b128 v[214:217], v141 offset:38912
	ds_read_b128 v[218:221], v141 offset:39936
	global_load_lds_dwordx4 v[230:231], off
	v_lshl_add_u64 v[230:231], s[40:41], 0, v[132:133]
	s_mov_b32 m0, s25
	s_nop 0
	global_load_lds_dwordx4 v[230:231], off
	s_waitcnt vmcnt(8)
	s_cmp_lt_u32 s32, 0x100
	s_cbranch_scc1 .Llgk_skip_18
	s_waitcnt lgkmcnt(0)
.Llgk_skip_18:
	s_barrier
	s_waitcnt lgkmcnt(0)
	v_mfma_f32_16x16x32_bf16 v[122:125], v[142:145], v[174:177], v[122:125]
	v_mfma_f32_16x16x32_bf16 v[126:129], v[150:153], v[174:177], v[126:129]
	v_mfma_f32_16x16x32_bf16 v[110:113], v[142:145], v[184:187], v[110:113]
	v_mfma_f32_16x16x32_bf16 v[106:109], v[150:153], v[184:187], v[106:109]
	v_mfma_f32_16x16x32_bf16 v[94:97], v[142:145], v[196:199], v[94:97]
	v_mfma_f32_16x16x32_bf16 v[90:93], v[150:153], v[196:199], v[90:93]
	v_mfma_f32_16x16x32_bf16 v[78:81], v[142:145], v[214:217], v[78:81]
	v_mfma_f32_16x16x32_bf16 v[74:77], v[150:153], v[214:217], v[74:77]
	v_mfma_f32_16x16x32_bf16 v[122:125], v[146:149], v[178:181], v[122:125]
	v_mfma_f32_16x16x32_bf16 v[126:129], v[154:157], v[178:181], v[126:129]
	v_mfma_f32_16x16x32_bf16 v[110:113], v[146:149], v[188:191], v[110:113]
	v_mfma_f32_16x16x32_bf16 v[106:109], v[154:157], v[188:191], v[106:109]
	v_mfma_f32_16x16x32_bf16 v[94:97], v[146:149], v[210:213], v[94:97]
	v_mfma_f32_16x16x32_bf16 v[90:93], v[154:157], v[210:213], v[90:93]
	v_mfma_f32_16x16x32_bf16 v[78:81], v[146:149], v[218:221], v[78:81]
	v_mfma_f32_16x16x32_bf16 v[74:77], v[154:157], v[218:221], v[74:77]
	v_mfma_f32_16x16x32_bf16 v[118:121], v[158:161], v[174:177], v[118:121]
	v_mfma_f32_16x16x32_bf16 v[114:117], v[166:169], v[174:177], v[114:117]
	v_mfma_f32_16x16x32_bf16 v[102:105], v[158:161], v[184:187], v[102:105]
	v_mfma_f32_16x16x32_bf16 v[98:101], v[166:169], v[184:187], v[98:101]
	v_mfma_f32_16x16x32_bf16 v[86:89], v[158:161], v[196:199], v[86:89]
	v_mfma_f32_16x16x32_bf16 v[82:85], v[166:169], v[196:199], v[82:85]
	v_mfma_f32_16x16x32_bf16 v[70:73], v[158:161], v[214:217], v[70:73]
	v_mfma_f32_16x16x32_bf16 v[66:69], v[166:169], v[214:217], v[66:69]
	v_mfma_f32_16x16x32_bf16 v[118:121], v[162:165], v[178:181], v[118:121]
	v_mfma_f32_16x16x32_bf16 v[114:117], v[170:173], v[178:181], v[114:117]
	v_mfma_f32_16x16x32_bf16 v[102:105], v[162:165], v[188:191], v[102:105]
	v_mfma_f32_16x16x32_bf16 v[98:101], v[170:173], v[188:191], v[98:101]
	v_mfma_f32_16x16x32_bf16 v[86:89], v[162:165], v[210:213], v[86:89]
	v_mfma_f32_16x16x32_bf16 v[82:85], v[170:173], v[210:213], v[82:85]
	v_mfma_f32_16x16x32_bf16 v[70:73], v[162:165], v[218:221], v[70:73]
	v_mfma_f32_16x16x32_bf16 v[66:69], v[170:173], v[218:221], v[66:69]
	s_barrier
	s_add_i32 s40, s53, s17
	v_lshl_add_u64 v[192:193], v[192:193], 0, s[22:23]
	s_mov_b32 m0, s40
	ds_read_b128 v[174:177], v141 offset:49152
	ds_read_b128 v[178:181], v141 offset:50176
	ds_read_b128 v[184:187], v141 offset:51200
	ds_read_b128 v[188:191], v141 offset:52224
	ds_read_b128 v[196:199], v141 offset:53248
	ds_read_b128 v[210:213], v141 offset:54272
	ds_read_b128 v[214:217], v141 offset:55296
	ds_read_b128 v[218:221], v141 offset:56320
	global_load_lds_dwordx4 v[192:193], off
	v_lshl_add_u64 v[192:193], v[202:203], 0, s[22:23]
	s_add_i32 m0, s40, 0x2000
	s_add_i32 s40, s54, s17
	global_load_lds_dwordx4 v[192:193], off
	v_lshl_add_u64 v[192:193], v[222:223], 0, s[22:23]
	s_mov_b32 m0, s40
	s_nop 0
	global_load_lds_dwordx4 v[192:193], off
	v_lshl_add_u64 v[192:193], v[224:225], 0, s[22:23]
	s_add_i32 m0, s40, 0x2000
	s_nop 0
	global_load_lds_dwordx4 v[192:193], off
	v_lshl_add_u64 v[192:193], v[226:227], 0, s[22:23]
	s_mov_b32 m0, s42
	s_nop 0
	global_load_lds_dwordx4 v[192:193], off
	v_lshl_add_u64 v[192:193], v[228:229], 0, s[22:23]
	s_mov_b32 m0, s43
	s_nop 0
	global_load_lds_dwordx4 v[192:193], off
	s_waitcnt vmcnt(8)
	s_cmp_lt_u32 s32, 0x100
	s_cbranch_scc1 .Llgk_skip_19
	s_waitcnt lgkmcnt(0)
.Llgk_skip_19:
	s_barrier
	s_waitcnt lgkmcnt(0)
	v_mfma_f32_16x16x32_bf16 v[62:65], v[142:145], v[174:177], v[62:65]
	v_mfma_f32_16x16x32_bf16 v[58:61], v[150:153], v[174:177], v[58:61]
	v_mfma_f32_16x16x32_bf16 v[46:49], v[142:145], v[184:187], v[46:49]
	v_mfma_f32_16x16x32_bf16 v[42:45], v[150:153], v[184:187], v[42:45]
	v_mfma_f32_16x16x32_bf16 v[30:33], v[142:145], v[196:199], v[30:33]
	v_mfma_f32_16x16x32_bf16 v[26:29], v[150:153], v[196:199], v[26:29]
	v_mfma_f32_16x16x32_bf16 v[14:17], v[142:145], v[214:217], v[14:17]
	v_mfma_f32_16x16x32_bf16 v[10:13], v[150:153], v[214:217], v[10:13]
	v_mfma_f32_16x16x32_bf16 v[62:65], v[146:149], v[178:181], v[62:65]
	v_mfma_f32_16x16x32_bf16 v[58:61], v[154:157], v[178:181], v[58:61]
	v_mfma_f32_16x16x32_bf16 v[46:49], v[146:149], v[188:191], v[46:49]
	v_mfma_f32_16x16x32_bf16 v[42:45], v[154:157], v[188:191], v[42:45]
	v_mfma_f32_16x16x32_bf16 v[30:33], v[146:149], v[210:213], v[30:33]
	v_mfma_f32_16x16x32_bf16 v[26:29], v[154:157], v[210:213], v[26:29]
	v_mfma_f32_16x16x32_bf16 v[14:17], v[146:149], v[218:221], v[14:17]
	v_mfma_f32_16x16x32_bf16 v[10:13], v[154:157], v[218:221], v[10:13]
	v_mfma_f32_16x16x32_bf16 v[54:57], v[158:161], v[174:177], v[54:57]
	v_mfma_f32_16x16x32_bf16 v[50:53], v[166:169], v[174:177], v[50:53]
	v_mfma_f32_16x16x32_bf16 v[38:41], v[158:161], v[184:187], v[38:41]
	v_mfma_f32_16x16x32_bf16 v[34:37], v[166:169], v[184:187], v[34:37]
	v_mfma_f32_16x16x32_bf16 v[22:25], v[158:161], v[196:199], v[22:25]
	v_mfma_f32_16x16x32_bf16 v[18:21], v[166:169], v[196:199], v[18:21]
	v_mfma_f32_16x16x32_bf16 v[6:9], v[158:161], v[214:217], v[6:9]
	v_mfma_f32_16x16x32_bf16 v[2:5], v[166:169], v[214:217], v[2:5]
	v_mfma_f32_16x16x32_bf16 v[54:57], v[162:165], v[178:181], v[54:57]
	v_mfma_f32_16x16x32_bf16 v[50:53], v[170:173], v[178:181], v[50:53]
	v_mfma_f32_16x16x32_bf16 v[38:41], v[162:165], v[188:191], v[38:41]
	v_mfma_f32_16x16x32_bf16 v[34:37], v[170:173], v[188:191], v[34:37]
	v_mfma_f32_16x16x32_bf16 v[22:25], v[162:165], v[210:213], v[22:25]
	v_mfma_f32_16x16x32_bf16 v[18:21], v[170:173], v[210:213], v[18:21]
	v_mfma_f32_16x16x32_bf16 v[6:9], v[162:165], v[218:221], v[6:9]
	v_mfma_f32_16x16x32_bf16 v[2:5], v[170:173], v[218:221], v[2:5]
	s_barrier
	s_add_u32 s36, s36, 0x100
	s_addc_u32 s37, s37, 0
	s_add_u32 s50, s50, 0x100
	s_addc_u32 s51, s51, 0
	s_cmp_ge_i32 s52, s29
	s_mov_b32 s40, s52
	s_cbranch_scc0 .LBB0_957
	s_setprio 0

.Lsprio_5:
.LBB0_986:
	s_add_u32 s25, s12, 0xfffc0080
	s_addc_u32 s26, s13, -1
	s_add_i32 s28, 0, 0x10000
	s_cmp_eq_u32 s24, 12
	s_cselect_b32 s37, s3, s26
	s_cselect_b32 s36, s16, s25
	v_add_u32_e32 v144, s28, v147
	s_cselect_b32 s31, s15, s21
	s_cselect_b32 s30, s18, s19
	s_add_i32 s25, 0, 0x14000
	ds_read_b128 v[140:143], v144
	ds_read_b128 v[152:155], v144 offset:1024
	ds_read_b128 v[156:159], v144 offset:2048
	ds_read_b128 v[160:163], v144 offset:3072
	v_add_u32_e32 v144, s25, v147
	ds_read_b128 v[164:167], v144
	ds_read_b128 v[168:171], v144 offset:1024
	ds_read_b128 v[172:175], v144 offset:2048
	ds_read_b128 v[176:179], v144 offset:3072
	v_lshl_add_u64 v[144:145], s[12:13], 0, v[136:137]
	s_add_i32 m0, s47, 0xc000
	ds_read_b128 v[184:187], v150
	ds_read_b128 v[188:191], v150 offset:1024
	ds_read_b128 v[196:199], v150 offset:2048
	ds_read_b128 v[210:213], v150 offset:3072
	ds_read_b128 v[214:217], v150 offset:4096
	ds_read_b128 v[218:221], v150 offset:5120
	ds_read_b128 v[222:225], v150 offset:6144
	ds_read_b128 v[226:229], v150 offset:7168
	global_load_lds_dwordx4 v[144:145], off
	v_lshl_add_u64 v[144:145], s[12:13], 0, v[138:139]
	s_add_i32 m0, s47, 0xe000
	s_nop 0
	global_load_lds_dwordx4 v[144:145], off
	s_waitcnt vmcnt(8)
	s_cmp_lt_u32 s32, 0x100
	s_cbranch_scc1 .Llgk_skip_20
	s_waitcnt lgkmcnt(0)
.Llgk_skip_20:
	s_barrier
	s_waitcnt lgkmcnt(0)
	v_mfma_f32_16x16x32_bf16 v[126:129], v[140:143], v[184:187], v[126:129]
	v_mfma_f32_16x16x32_bf16 v[122:125], v[156:159], v[184:187], v[122:125]
	v_mfma_f32_16x16x32_bf16 v[110:113], v[140:143], v[196:199], v[110:113]
	v_mfma_f32_16x16x32_bf16 v[106:109], v[156:159], v[196:199], v[106:109]
	v_mfma_f32_16x16x32_bf16 v[94:97], v[140:143], v[214:217], v[94:97]
	v_mfma_f32_16x16x32_bf16 v[90:93], v[156:159], v[214:217], v[90:93]
	v_mfma_f32_16x16x32_bf16 v[78:81], v[140:143], v[222:225], v[78:81]
	v_mfma_f32_16x16x32_bf16 v[74:77], v[156:159], v[222:225], v[74:77]
	v_mfma_f32_16x16x32_bf16 v[126:129], v[152:155], v[188:191], v[126:129]
	v_mfma_f32_16x16x32_bf16 v[122:125], v[160:163], v[188:191], v[122:125]
	v_mfma_f32_16x16x32_bf16 v[110:113], v[152:155], v[210:213], v[110:113]
	v_mfma_f32_16x16x32_bf16 v[106:109], v[160:163], v[210:213], v[106:109]
	v_mfma_f32_16x16x32_bf16 v[94:97], v[152:155], v[218:221], v[94:97]
	v_mfma_f32_16x16x32_bf16 v[90:93], v[160:163], v[218:221], v[90:93]
	v_mfma_f32_16x16x32_bf16 v[78:81], v[152:155], v[226:229], v[78:81]
	v_mfma_f32_16x16x32_bf16 v[74:77], v[160:163], v[226:229], v[74:77]
	v_mfma_f32_16x16x32_bf16 v[118:121], v[164:167], v[184:187], v[118:121]
	v_mfma_f32_16x16x32_bf16 v[114:117], v[172:175], v[184:187], v[114:117]
	v_mfma_f32_16x16x32_bf16 v[102:105], v[164:167], v[196:199], v[102:105]
	v_mfma_f32_16x16x32_bf16 v[98:101], v[172:175], v[196:199], v[98:101]
	v_mfma_f32_16x16x32_bf16 v[86:89], v[164:167], v[214:217], v[86:89]
	v_mfma_f32_16x16x32_bf16 v[82:85], v[172:175], v[214:217], v[82:85]
	v_mfma_f32_16x16x32_bf16 v[70:73], v[164:167], v[222:225], v[70:73]
	v_mfma_f32_16x16x32_bf16 v[66:69], v[172:175], v[222:225], v[66:69]
	v_mfma_f32_16x16x32_bf16 v[118:121], v[168:171], v[188:191], v[118:121]
	v_mfma_f32_16x16x32_bf16 v[114:117], v[176:179], v[188:191], v[114:117]
	v_mfma_f32_16x16x32_bf16 v[102:105], v[168:171], v[210:213], v[102:105]
	v_mfma_f32_16x16x32_bf16 v[98:101], v[176:179], v[210:213], v[98:101]
	v_mfma_f32_16x16x32_bf16 v[86:89], v[168:171], v[218:221], v[86:89]
	v_mfma_f32_16x16x32_bf16 v[82:85], v[176:179], v[218:221], v[82:85]
	v_mfma_f32_16x16x32_bf16 v[70:73], v[168:171], v[226:229], v[70:73]
	v_mfma_f32_16x16x32_bf16 v[66:69], v[176:179], v[226:229], v[66:69]
	s_barrier
	s_add_i32 s26, s28, s17
	v_lshl_add_u64 v[144:145], s[30:31], 0, v[0:1]
	s_mov_b32 m0, s26
	ds_read_b128 v[184:187], v150 offset:16384
	ds_read_b128 v[188:191], v150 offset:17408
	ds_read_b128 v[196:199], v150 offset:18432
	ds_read_b128 v[210:213], v150 offset:19456
	ds_read_b128 v[214:217], v150 offset:20480
	ds_read_b128 v[218:221], v150 offset:21504
	ds_read_b128 v[222:225], v150 offset:22528
	ds_read_b128 v[226:229], v150 offset:23552
	global_load_lds_dwordx4 v[144:145], off
	s_add_i32 m0, s26, 0x2000
	s_add_u32 s60, s30, 0x40000
	v_lshl_add_u64 v[180:181], s[30:31], 0, v[130:131]
	s_addc_u32 s61, s31, 0
	s_add_i32 s25, s25, s17
	global_load_lds_dwordx4 v[180:181], off
	v_lshl_add_u64 v[192:193], s[60:61], 0, v[0:1]
	s_mov_b32 m0, s25
	v_lshl_add_u64 v[202:203], s[36:37], 0, v[132:133]
	global_load_lds_dwordx4 v[192:193], off
	v_lshl_add_u64 v[192:193], s[60:61], 0, v[130:131]
	s_add_i32 m0, s25, 0x2000
	s_nop 0
	global_load_lds_dwordx4 v[192:193], off
	v_lshl_add_u64 v[192:193], s[36:37], 0, v[134:135]
	s_mov_b32 m0, s47
	s_nop 0
	global_load_lds_dwordx4 v[192:193], off
	s_mov_b32 m0, s48
	s_nop 0
	global_load_lds_dwordx4 v[202:203], off
	s_waitcnt vmcnt(8)
	s_cmp_lt_u32 s32, 0x100
	s_cbranch_scc1 .Llgk_skip_21
	s_waitcnt lgkmcnt(0)
.Llgk_skip_21:
	s_barrier
	s_waitcnt lgkmcnt(0)
	v_mfma_f32_16x16x32_bf16 v[62:65], v[140:143], v[184:187], v[62:65]
	v_mfma_f32_16x16x32_bf16 v[58:61], v[156:159], v[184:187], v[58:61]
	v_mfma_f32_16x16x32_bf16 v[46:49], v[140:143], v[196:199], v[46:49]
	v_mfma_f32_16x16x32_bf16 v[42:45], v[156:159], v[196:199], v[42:45]
	v_mfma_f32_16x16x32_bf16 v[30:33], v[140:143], v[214:217], v[30:33]
	v_mfma_f32_16x16x32_bf16 v[26:29], v[156:159], v[214:217], v[26:29]
	v_mfma_f32_16x16x32_bf16 v[14:17], v[140:143], v[222:225], v[14:17]
	v_mfma_f32_16x16x32_bf16 v[10:13], v[156:159], v[222:225], v[10:13]
	v_mfma_f32_16x16x32_bf16 v[62:65], v[152:155], v[188:191], v[62:65]
	v_mfma_f32_16x16x32_bf16 v[58:61], v[160:163], v[188:191], v[58:61]
	v_mfma_f32_16x16x32_bf16 v[46:49], v[152:155], v[210:213], v[46:49]
	v_mfma_f32_16x16x32_bf16 v[42:45], v[160:163], v[210:213], v[42:45]
	v_mfma_f32_16x16x32_bf16 v[30:33], v[152:155], v[218:221], v[30:33]
	v_mfma_f32_16x16x32_bf16 v[26:29], v[160:163], v[218:221], v[26:29]
	v_mfma_f32_16x16x32_bf16 v[14:17], v[152:155], v[226:229], v[14:17]
	v_mfma_f32_16x16x32_bf16 v[10:13], v[160:163], v[226:229], v[10:13]
	v_mfma_f32_16x16x32_bf16 v[54:57], v[164:167], v[184:187], v[54:57]
	v_mfma_f32_16x16x32_bf16 v[50:53], v[172:175], v[184:187], v[50:53]
	v_mfma_f32_16x16x32_bf16 v[38:41], v[164:167], v[196:199], v[38:41]
	v_mfma_f32_16x16x32_bf16 v[34:37], v[172:175], v[196:199], v[34:37]
	v_mfma_f32_16x16x32_bf16 v[22:25], v[164:167], v[214:217], v[22:25]
	v_mfma_f32_16x16x32_bf16 v[18:21], v[172:175], v[214:217], v[18:21]
	v_mfma_f32_16x16x32_bf16 v[6:9], v[164:167], v[222:225], v[6:9]
	v_mfma_f32_16x16x32_bf16 v[2:5], v[172:175], v[222:225], v[2:5]
	v_mfma_f32_16x16x32_bf16 v[54:57], v[168:171], v[188:191], v[54:57]
	v_mfma_f32_16x16x32_bf16 v[50:53], v[176:179], v[188:191], v[50:53]
	v_mfma_f32_16x16x32_bf16 v[38:41], v[168:171], v[210:213], v[38:41]
	v_mfma_f32_16x16x32_bf16 v[34:37], v[176:179], v[210:213], v[34:37]
	v_mfma_f32_16x16x32_bf16 v[22:25], v[168:171], v[218:221], v[22:25]
	v_mfma_f32_16x16x32_bf16 v[18:21], v[176:179], v[218:221], v[18:21]
	v_mfma_f32_16x16x32_bf16 v[6:9], v[168:171], v[226:229], v[6:9]
	v_mfma_f32_16x16x32_bf16 v[2:5], v[176:179], v[226:229], v[2:5]
	s_barrier
	s_add_i32 s25, 0, 0x18000
	v_add_u32_e32 v151, s25, v147
	s_add_i32 s26, 0, 0x1c000
	ds_read_b128 v[140:143], v151
	ds_read_b128 v[152:155], v151 offset:1024
	ds_read_b128 v[156:159], v151 offset:2048
	ds_read_b128 v[160:163], v151 offset:3072
	v_add_u32_e32 v151, s26, v147
	ds_read_b128 v[164:167], v151
	ds_read_b128 v[168:171], v151 offset:1024
	ds_read_b128 v[172:175], v151 offset:2048
	ds_read_b128 v[176:179], v151 offset:3072
	s_add_u32 s36, s36, 0x40000
	s_addc_u32 s37, s37, 0
	s_mov_b32 m0, s49
	v_lshl_add_u64 v[230:231], s[36:37], 0, v[134:135]
	ds_read_b128 v[184:187], v150 offset:32768
	ds_read_b128 v[188:191], v150 offset:33792
	ds_read_b128 v[196:199], v150 offset:34816
	ds_read_b128 v[210:213], v150 offset:35840
	ds_read_b128 v[214:217], v150 offset:36864
	ds_read_b128 v[218:221], v150 offset:37888
	ds_read_b128 v[222:225], v150 offset:38912
	ds_read_b128 v[226:229], v150 offset:39936
	global_load_lds_dwordx4 v[230:231], off
	v_lshl_add_u64 v[230:231], s[36:37], 0, v[132:133]
	s_mov_b32 m0, s50
	s_nop 0
	global_load_lds_dwordx4 v[230:231], off
	s_waitcnt vmcnt(8)
	s_cmp_lt_u32 s32, 0x100
	s_cbranch_scc1 .Llgk_skip_22
	s_waitcnt lgkmcnt(0)
.Llgk_skip_22:
	s_barrier
	s_waitcnt lgkmcnt(0)
	v_mfma_f32_16x16x32_bf16 v[126:129], v[140:143], v[184:187], v[126:129]
	v_mfma_f32_16x16x32_bf16 v[122:125], v[156:159], v[184:187], v[122:125]
	v_mfma_f32_16x16x32_bf16 v[110:113], v[140:143], v[196:199], v[110:113]
	v_mfma_f32_16x16x32_bf16 v[106:109], v[156:159], v[196:199], v[106:109]
	v_mfma_f32_16x16x32_bf16 v[94:97], v[140:143], v[214:217], v[94:97]
	v_mfma_f32_16x16x32_bf16 v[90:93], v[156:159], v[214:217], v[90:93]
	v_mfma_f32_16x16x32_bf16 v[78:81], v[140:143], v[222:225], v[78:81]
	v_mfma_f32_16x16x32_bf16 v[74:77], v[156:159], v[222:225], v[74:77]
	v_mfma_f32_16x16x32_bf16 v[126:129], v[152:155], v[188:191], v[126:129]
	v_mfma_f32_16x16x32_bf16 v[122:125], v[160:163], v[188:191], v[122:125]
	v_mfma_f32_16x16x32_bf16 v[110:113], v[152:155], v[210:213], v[110:113]
	v_mfma_f32_16x16x32_bf16 v[106:109], v[160:163], v[210:213], v[106:109]
	v_mfma_f32_16x16x32_bf16 v[94:97], v[152:155], v[218:221], v[94:97]
	v_mfma_f32_16x16x32_bf16 v[90:93], v[160:163], v[218:221], v[90:93]
	v_mfma_f32_16x16x32_bf16 v[78:81], v[152:155], v[226:229], v[78:81]
	v_mfma_f32_16x16x32_bf16 v[74:77], v[160:163], v[226:229], v[74:77]
	v_mfma_f32_16x16x32_bf16 v[118:121], v[164:167], v[184:187], v[118:121]
	v_mfma_f32_16x16x32_bf16 v[114:117], v[172:175], v[184:187], v[114:117]
	v_mfma_f32_16x16x32_bf16 v[102:105], v[164:167], v[196:199], v[102:105]
	v_mfma_f32_16x16x32_bf16 v[98:101], v[172:175], v[196:199], v[98:101]
	v_mfma_f32_16x16x32_bf16 v[86:89], v[164:167], v[214:217], v[86:89]
	v_mfma_f32_16x16x32_bf16 v[82:85], v[172:175], v[214:217], v[82:85]
	v_mfma_f32_16x16x32_bf16 v[70:73], v[164:167], v[222:225], v[70:73]
	v_mfma_f32_16x16x32_bf16 v[66:69], v[172:175], v[222:225], v[66:69]
	v_mfma_f32_16x16x32_bf16 v[118:121], v[168:171], v[188:191], v[118:121]
	v_mfma_f32_16x16x32_bf16 v[114:117], v[176:179], v[188:191], v[114:117]
	v_mfma_f32_16x16x32_bf16 v[102:105], v[168:171], v[210:213], v[102:105]
	v_mfma_f32_16x16x32_bf16 v[98:101], v[176:179], v[210:213], v[98:101]
	v_mfma_f32_16x16x32_bf16 v[86:89], v[168:171], v[218:221], v[86:89]
	v_mfma_f32_16x16x32_bf16 v[82:85], v[176:179], v[218:221], v[82:85]
	v_mfma_f32_16x16x32_bf16 v[70:73], v[168:171], v[226:229], v[70:73]
	v_mfma_f32_16x16x32_bf16 v[66:69], v[176:179], v[226:229], v[66:69]
	s_barrier
	s_add_i32 s25, s25, s17
	v_lshl_add_u64 v[144:145], v[144:145], 0, s[22:23]
	s_mov_b32 m0, s25
	ds_read_b128 v[184:187], v150 offset:49152
	ds_read_b128 v[188:191], v150 offset:50176
	ds_read_b128 v[196:199], v150 offset:51200
	ds_read_b128 v[210:213], v150 offset:52224
	ds_read_b128 v[214:217], v150 offset:53248
	ds_read_b128 v[218:221], v150 offset:54272
	ds_read_b128 v[222:225], v150 offset:55296
	ds_read_b128 v[226:229], v150 offset:56320
	global_load_lds_dwordx4 v[144:145], off
	s_add_i32 m0, s25, 0x2000
	s_add_u32 s30, s30, 0x40080
	v_lshl_add_u64 v[144:145], v[180:181], 0, s[22:23]
	s_addc_u32 s31, s31, 0
	s_add_i32 s25, s26, s17
	global_load_lds_dwordx4 v[144:145], off
	v_lshl_add_u64 v[144:145], s[30:31], 0, v[0:1]
	s_mov_b32 m0, s25
	s_nop 0
	global_load_lds_dwordx4 v[144:145], off
	v_lshl_add_u64 v[144:145], s[30:31], 0, v[130:131]
	s_add_i32 m0, s25, 0x2000
	s_nop 0
	global_load_lds_dwordx4 v[144:145], off
	v_lshl_add_u64 v[144:145], v[192:193], 0, s[22:23]
	s_mov_b32 m0, s54
	s_nop 0
	global_load_lds_dwordx4 v[144:145], off
	v_lshl_add_u64 v[144:145], v[202:203], 0, s[22:23]
	s_mov_b32 m0, s55
	s_nop 0
	global_load_lds_dwordx4 v[144:145], off
	s_waitcnt vmcnt(8)
	s_cmp_lt_u32 s32, 0x100
	s_cbranch_scc1 .Llgk_skip_23
	s_waitcnt lgkmcnt(0)
.Llgk_skip_23:
	s_barrier
	s_waitcnt lgkmcnt(0)
	v_mfma_f32_16x16x32_bf16 v[62:65], v[140:143], v[184:187], v[62:65]
	v_mfma_f32_16x16x32_bf16 v[58:61], v[156:159], v[184:187], v[58:61]
	v_mfma_f32_16x16x32_bf16 v[46:49], v[140:143], v[196:199], v[46:49]
	v_mfma_f32_16x16x32_bf16 v[42:45], v[156:159], v[196:199], v[42:45]
	v_mfma_f32_16x16x32_bf16 v[30:33], v[140:143], v[214:217], v[30:33]
	v_mfma_f32_16x16x32_bf16 v[26:29], v[156:159], v[214:217], v[26:29]
	v_mfma_f32_16x16x32_bf16 v[14:17], v[140:143], v[222:225], v[14:17]
	v_mfma_f32_16x16x32_bf16 v[10:13], v[156:159], v[222:225], v[10:13]
	v_mfma_f32_16x16x32_bf16 v[62:65], v[152:155], v[188:191], v[62:65]
	v_mfma_f32_16x16x32_bf16 v[58:61], v[160:163], v[188:191], v[58:61]
	v_mfma_f32_16x16x32_bf16 v[46:49], v[152:155], v[210:213], v[46:49]
	v_mfma_f32_16x16x32_bf16 v[42:45], v[160:163], v[210:213], v[42:45]
	v_mfma_f32_16x16x32_bf16 v[30:33], v[152:155], v[218:221], v[30:33]
	v_mfma_f32_16x16x32_bf16 v[26:29], v[160:163], v[218:221], v[26:29]
	v_mfma_f32_16x16x32_bf16 v[14:17], v[152:155], v[226:229], v[14:17]
	v_mfma_f32_16x16x32_bf16 v[10:13], v[160:163], v[226:229], v[10:13]
	v_mfma_f32_16x16x32_bf16 v[54:57], v[164:167], v[184:187], v[54:57]
	v_mfma_f32_16x16x32_bf16 v[50:53], v[172:175], v[184:187], v[50:53]
	v_mfma_f32_16x16x32_bf16 v[38:41], v[164:167], v[196:199], v[38:41]
	v_mfma_f32_16x16x32_bf16 v[34:37], v[172:175], v[196:199], v[34:37]
	v_mfma_f32_16x16x32_bf16 v[22:25], v[164:167], v[214:217], v[22:25]
	v_mfma_f32_16x16x32_bf16 v[18:21], v[172:175], v[214:217], v[18:21]
	v_mfma_f32_16x16x32_bf16 v[6:9], v[164:167], v[222:225], v[6:9]
	v_mfma_f32_16x16x32_bf16 v[2:5], v[172:175], v[222:225], v[2:5]
	v_mfma_f32_16x16x32_bf16 v[54:57], v[168:171], v[188:191], v[54:57]
	v_mfma_f32_16x16x32_bf16 v[50:53], v[176:179], v[188:191], v[50:53]
	v_mfma_f32_16x16x32_bf16 v[38:41], v[168:171], v[210:213], v[38:41]
	v_mfma_f32_16x16x32_bf16 v[34:37], v[176:179], v[210:213], v[34:37]
	v_mfma_f32_16x16x32_bf16 v[22:25], v[168:171], v[218:221], v[22:25]
	v_mfma_f32_16x16x32_bf16 v[18:21], v[176:179], v[218:221], v[18:21]
	v_mfma_f32_16x16x32_bf16 v[6:9], v[168:171], v[226:229], v[6:9]
	v_mfma_f32_16x16x32_bf16 v[2:5], v[176:179], v[226:229], v[2:5]
	s_barrier
	s_add_i32 s24, s24, 2
	s_add_u32 s12, s12, 0x100
	s_addc_u32 s13, s13, 0
	s_add_u32 s19, s19, 0x100
	s_addc_u32 s21, s21, 0
	s_cmp_gt_u32 s24, 13
	s_cbranch_scc0 .LBB0_986
	s_setprio 0
	s_and_b64 vcc, exec, s[10:11]
	s_cbranch_vccz .LBB0_989
	s_barrier
